# speedup vs baseline: 1.0545x; 1.0040x over previous
;     ...
;   for (int kt = 0; kt < nk; ++kt) {
;     const int kn = (kt + 1 < nk) ? kt + 1 : kt;
;     GM_LOAD2(kn * 64, kn * bkstep)
;     __builtin_amdgcn_sched_barrier(0);
;     const char* As = smem + (kt & 1) * 2 * TILE_B;
;     const char* Bs = As + TILE_B;
;     if constexpr (HOIST) {
;       bf16x8 fa0[4], fa1[4], fb0[4], fb1[4];
; #pragma unroll
;       for (int st = 0; st < 4; ++st) {
;         fa0[st] = *(const bf16x8*)(As + aoff + st * 32);
;         fb0[st] = *(const bf16x8*)(Bs + boff + st * 32);
;         fa1[st] = *(const bf16x8*)(As + aoff + 32 * LSTR + st * 32);
;         fb1[st] = *(const bf16x8*)(Bs + boff + 32 * LSTR + st * 32);
;       }
;       __builtin_amdgcn_sched_barrier(0);
; #pragma unroll
;       for (int st = 0; st < 4; ++st) {
;         acc[0][0] = mfma32(fa0[st], fb0[st], acc[0][0]);
;         acc[0][1] = mfma32(fa0[st], fb1[st], acc[0][1]);
;         acc[1][0] = mfma32(fa1[st], fb0[st], acc[1][0]);
;         acc[1][1] = mfma32(fa1[st], fb1[st], acc[1][1]);
;       }
;     } else {
; #pragma unroll
;       for (int st = 0; st < 4; ++st) {
;         bf16x8 a0 = *(const bf16x8*)(As + aoff + st * 32);
;         bf16x8 a1 = *(const bf16x8*)(As + aoff + 32 * LSTR + st * 32);
;         bf16x8 b0 = *(const bf16x8*)(Bs + boff + st * 32);
;         bf16x8 b1 = *(const bf16x8*)(Bs + boff + 32 * LSTR + st * 32);
;         acc[0][0] = mfma32(a0, b0, acc[0][0]);
;         acc[0][1] = mfma32(a0, b1, acc[0][1]);
;         acc[1][0] = mfma32(a1, b0, acc[1][0]);
;         acc[1][1] = mfma32(a1, b1, acc[1][1]);
;       }
;     }
;     __builtin_amdgcn_sched_barrier(0);
;     {
;       char* Ad = smem + ((kt + 1) & 1) * 2 * TILE_B;
;       GM_STORE(Ad)
;     }
;     __syncthreads();
.LBB0_360:
	s_and_b32 s25, s14, 2
	s_mulk_i32 s25, 0x4800
	v_add3_u32 v197, s25, v191, v192
	s_setprio 1
	v_add3_u32 v223, s25, v193, v192
	ds_read_b128 v[232:235], v197 offset:0
	ds_read_b128 v[236:239], v223 offset:18432
	ds_read_b128 v[244:247], v197 offset:4608
	ds_read_b128 v[240:243], v223 offset:23040
	s_waitcnt lgkmcnt(2)
	v_mfma_f32_32x32x16_bf16 v[50:65], v[232:235], v[236:239], v[50:65]
	ds_read_b128 v[248:251], v197 offset:32
	s_waitcnt lgkmcnt(2)
	v_mfma_f32_32x32x16_bf16 v[2:17], v[244:247], v[236:239], v[2:17]
	ds_read_b128 v[236:239], v223 offset:18464
	s_waitcnt lgkmcnt(2)
	v_mfma_f32_32x32x16_bf16 v[18:33], v[232:235], v[240:243], v[18:33]
	ds_read_b128 v[232:235], v197 offset:4640
	v_mfma_f32_32x32x16_bf16 v[34:49], v[244:247], v[240:243], v[34:49]
	ds_read_b128 v[240:243], v223 offset:23072
	s_waitcnt lgkmcnt(2)
	v_mfma_f32_32x32x16_bf16 v[50:65], v[248:251], v[236:239], v[50:65]
	ds_read_b128 v[244:247], v197 offset:64
	s_waitcnt lgkmcnt(2)
	v_mfma_f32_32x32x16_bf16 v[2:17], v[232:235], v[236:239], v[2:17]
	ds_read_b128 v[236:239], v223 offset:18496
	s_waitcnt lgkmcnt(2)
	v_mfma_f32_32x32x16_bf16 v[18:33], v[248:251], v[240:243], v[18:33]
	ds_read_b128 v[248:251], v197 offset:4672
	v_mfma_f32_32x32x16_bf16 v[34:49], v[232:235], v[240:243], v[34:49]
	ds_read_b128 v[240:243], v223 offset:23104
	s_waitcnt lgkmcnt(2)
	v_mfma_f32_32x32x16_bf16 v[50:65], v[244:247], v[236:239], v[50:65]
	ds_read_b128 v[232:235], v197 offset:96
	s_waitcnt lgkmcnt(2)
	v_mfma_f32_32x32x16_bf16 v[2:17], v[248:251], v[236:239], v[2:17]
	ds_read_b128 v[236:239], v223 offset:18528
	s_waitcnt lgkmcnt(2)
	v_mfma_f32_32x32x16_bf16 v[18:33], v[244:247], v[240:243], v[18:33]
	ds_read_b128 v[244:247], v197 offset:4704
	v_mfma_f32_32x32x16_bf16 v[34:49], v[248:251], v[240:243], v[34:49]
	ds_read_b128 v[240:243], v223 offset:23136
	s_waitcnt lgkmcnt(2)
	v_mfma_f32_32x32x16_bf16 v[50:65], v[232:235], v[236:239], v[50:65]
	s_waitcnt lgkmcnt(1)
	v_mfma_f32_32x32x16_bf16 v[2:17], v[244:247], v[236:239], v[2:17]
	s_waitcnt lgkmcnt(0)
	v_mfma_f32_32x32x16_bf16 v[18:33], v[232:235], v[240:243], v[18:33]
	v_mfma_f32_32x32x16_bf16 v[34:49], v[244:247], v[240:243], v[34:49]
	s_setprio 0
	s_add_i32 s14, s14, 2
	s_and_b32 s25, s14, 2
	s_mulk_i32 s25, 0x4800
	s_add_i32 s15, s15, -1
	s_add_i32 s6, s6, 64
	v_add_u32_e32 v197, s25, v190
	s_lshl_b64 s[26:27], s[6:7], 1
	s_cmp_lg_u32 s15, 0
	s_waitcnt vmcnt(7)
	ds_write_b128 v197, v[198:201]
	v_lshl_add_u64 v[198:199], v[158:159], 0, s[26:27]
	global_load_dwordx4 v[198:201], v[198:199], off
	s_waitcnt vmcnt(7)
	ds_write_b128 v197, v[202:205] offset:4608
	v_lshl_add_u64 v[202:203], v[160:161], 0, s[26:27]
	global_load_dwordx4 v[202:205], v[202:203], off
	s_waitcnt vmcnt(7)
	ds_write_b128 v197, v[206:209] offset:9216
	v_lshl_add_u64 v[206:207], v[162:163], 0, s[26:27]
	global_load_dwordx4 v[206:209], v[206:207], off
	s_waitcnt vmcnt(7)
	ds_write_b128 v197, v[210:213] offset:13824
	v_lshl_add_u64 v[210:211], v[164:165], 0, s[26:27]
	global_load_dwordx4 v[210:213], v[210:211], off
	s_waitcnt vmcnt(7)
	ds_write_b128 v197, v[214:217] offset:18432
	v_lshl_add_u64 v[214:215], v[166:167], 0, s[26:27]
	global_load_dwordx4 v[214:217], v[214:215], off
	s_waitcnt vmcnt(7)
	ds_write_b128 v197, v[218:221] offset:23040
	v_lshl_add_u64 v[218:219], v[168:169], 0, s[26:27]
	global_load_dwordx4 v[218:221], v[218:219], off
	s_waitcnt vmcnt(7)
	ds_write_b128 v197, v[224:227] offset:27648
	v_lshl_add_u64 v[224:225], v[170:171], 0, s[26:27]
	global_load_dwordx4 v[224:227], v[224:225], off
	s_waitcnt vmcnt(7)
	ds_write_b128 v197, v[228:231] offset:32256
	v_lshl_add_u64 v[228:229], v[172:173], 0, s[26:27]
	global_load_dwordx4 v[228:231], v[228:229], off
	s_waitcnt lgkmcnt(0)
	s_barrier
	s_cbranch_scc1 .LBB0_360
	s_and_b32 s25, s14, 2
	s_mulk_i32 s25, 0x4800
	v_add3_u32 v197, s25, v191, v192
	s_setprio 1
	v_add3_u32 v223, s25, v193, v192
	ds_read_b128 v[232:235], v197 offset:0
	ds_read_b128 v[236:239], v223 offset:18432
	ds_read_b128 v[244:247], v197 offset:4608
	ds_read_b128 v[240:243], v223 offset:23040
	s_waitcnt lgkmcnt(2)
	v_mfma_f32_32x32x16_bf16 v[50:65], v[232:235], v[236:239], v[50:65]
	ds_read_b128 v[248:251], v197 offset:32
	s_waitcnt lgkmcnt(2)
	v_mfma_f32_32x32x16_bf16 v[2:17], v[244:247], v[236:239], v[2:17]
	ds_read_b128 v[236:239], v223 offset:18464
	s_waitcnt lgkmcnt(2)
	v_mfma_f32_32x32x16_bf16 v[18:33], v[232:235], v[240:243], v[18:33]
	ds_read_b128 v[232:235], v197 offset:4640
	v_mfma_f32_32x32x16_bf16 v[34:49], v[244:247], v[240:243], v[34:49]
	ds_read_b128 v[240:243], v223 offset:23072
	s_waitcnt lgkmcnt(2)
	v_mfma_f32_32x32x16_bf16 v[50:65], v[248:251], v[236:239], v[50:65]
	ds_read_b128 v[244:247], v197 offset:64
	s_waitcnt lgkmcnt(2)
	v_mfma_f32_32x32x16_bf16 v[2:17], v[232:235], v[236:239], v[2:17]
	ds_read_b128 v[236:239], v223 offset:18496
	s_waitcnt lgkmcnt(2)
	v_mfma_f32_32x32x16_bf16 v[18:33], v[248:251], v[240:243], v[18:33]
	ds_read_b128 v[248:251], v197 offset:4672
	v_mfma_f32_32x32x16_bf16 v[34:49], v[232:235], v[240:243], v[34:49]
	ds_read_b128 v[240:243], v223 offset:23104
	s_waitcnt lgkmcnt(2)
	v_mfma_f32_32x32x16_bf16 v[50:65], v[244:247], v[236:239], v[50:65]
	ds_read_b128 v[232:235], v197 offset:96
	s_waitcnt lgkmcnt(2)
	v_mfma_f32_32x32x16_bf16 v[2:17], v[248:251], v[236:239], v[2:17]
	ds_read_b128 v[236:239], v223 offset:18528
	s_waitcnt lgkmcnt(2)
	v_mfma_f32_32x32x16_bf16 v[18:33], v[244:247], v[240:243], v[18:33]
	ds_read_b128 v[244:247], v197 offset:4704
	v_mfma_f32_32x32x16_bf16 v[34:49], v[248:251], v[240:243], v[34:49]
	ds_read_b128 v[240:243], v223 offset:23136
	s_waitcnt lgkmcnt(2)
	v_mfma_f32_32x32x16_bf16 v[50:65], v[232:235], v[236:239], v[50:65]
	s_waitcnt lgkmcnt(1)
	v_mfma_f32_32x32x16_bf16 v[2:17], v[244:247], v[236:239], v[2:17]
	s_waitcnt lgkmcnt(0)
	v_mfma_f32_32x32x16_bf16 v[18:33], v[232:235], v[240:243], v[18:33]
	v_mfma_f32_32x32x16_bf16 v[34:49], v[244:247], v[240:243], v[34:49]
	s_setprio 0
	s_add_i32 s14, s14, 2
	s_and_b32 s25, s14, 2
	s_mulk_i32 s25, 0x4800
	s_add_i32 s6, s6, 64
	v_add_u32_e32 v197, s25, v190
	s_waitcnt vmcnt(7)
	ds_write_b128 v197, v[198:201]
	s_waitcnt vmcnt(6)
	ds_write_b128 v197, v[202:205] offset:4608
	s_waitcnt vmcnt(5)
	ds_write_b128 v197, v[206:209] offset:9216
	s_waitcnt vmcnt(4)
	ds_write_b128 v197, v[210:213] offset:13824
	s_waitcnt vmcnt(3)
	ds_write_b128 v197, v[214:217] offset:18432
	s_waitcnt vmcnt(2)
	ds_write_b128 v197, v[218:221] offset:23040
	s_waitcnt vmcnt(1)
	ds_write_b128 v197, v[224:227] offset:27648
	s_waitcnt vmcnt(0)
	ds_write_b128 v197, v[228:231] offset:32256
	s_waitcnt lgkmcnt(0)
	s_barrier
;     ...
;         acc[0][0] = mfma32(fa0[st], fb0[st], acc[0][0]);
;         acc[0][1] = mfma32(fa0[st], fb1[st], acc[0][1]);
;         acc[1][0] = mfma32(fa1[st], fb0[st], acc[1][0]);
;         acc[1][1] = mfma32(fa1[st], fb1[st], acc[1][1]);
;       }
;     } else {
; #pragma unroll
;       for (int st = 0; st < 4; ++st) {
;         bf16x8 a0 = *(const bf16x8*)(As + aoff + st * 32);
;         bf16x8 a1 = *(const bf16x8*)(As + aoff + 32 * LSTR + st * 32);
;         bf16x8 b0 = *(const bf16x8*)(Bs + boff + st * 32);
;         bf16x8 b1 = *(const bf16x8*)(Bs + boff + 32 * LSTR + st * 32);
;         acc[0][0] = mfma32(a0, b0, acc[0][0]);
;         acc[0][1] = mfma32(a0, b1, acc[0][1]);
;         acc[1][0] = mfma32(a1, b0, acc[1][0]);
;         acc[1][1] = mfma32(a1, b1, acc[1][1]);
; __device__ __forceinline__ void acc_to_lds(const f32x16 (&acc)[2][2], float* cs) {
;   const int tid = threadIdx.x, lane = tid & 63, wave = tid >> 6;
;   const int wm = wave >> 1, wn = wave & 1;
; #pragma unroll
;   for (int i = 0; i < 2; ++i)
; #pragma unroll
;     for (int j = 0; j < 2; ++j)
; #pragma unroll
;       for (int r = 0; r < 16; ++r) {
;         int row = wm * 64 + i * 32 + (r & 3) + 8 * (r >> 2) + 4 * (lane >> 5);
;         int col = wn * 64 + j * 32 + (lane & 31);
;         cs[row * CSTR + col] = acc[i][j][r];
;       }
;   __syncthreads();
; __device__ __forceinline__ void fourier_half_tile(const Params& P, bool isctx, int b, int mt, int nt, char* smem) {
;     ...
;       for (int q = 0; q < 8; ++q) {
;         float4 a = *(const float4*)(cs + r * CSTR + half * 64 + q * 8);
;         float4 c = *(const float4*)(cs + r * CSTR + half * 64 + q * 8 + 4);
;         uint4 o1, o2;
;         o1.x = pack2(pacc[q * 8 + 0] + a.x, pacc[q * 8 + 1] + a.y); o1.y = pack2(pacc[q * 8 + 2] + a.z, pacc[q * 8 + 3] + a.w);
;         o1.z = pack2(pacc[q * 8 + 4] + c.x, pacc[q * 8 + 5] + c.y); o1.w = pack2(pacc[q * 8 + 6] + c.z, pacc[q * 8 + 7] + c.w);
;         o2.x = pack2(pacc[q * 8 + 0] - a.x, pacc[q * 8 + 1] - a.y); o2.y = pack2(pacc[q * 8 + 2] - a.z, pacc[q * 8 + 3] - a.w);
;         o2.z = pack2(pacc[q * 8 + 4] - c.x, pacc[q * 8 + 5] - c.y); o2.w = pack2(pacc[q * 8 + 6] - c.z, pacc[q * 8 + 7] - c.w);
;         *(uint4*)(d1 + q * 8) = o1;
;         if (k > 0) *(uint4*)(d2 + q * 8) = o2;
	s_nop 0
	s_nop 0
	s_nop 0
	v_add3_u32 v197, s25, v191, v192
	s_setprio 1
	v_add3_u32 v223, s25, v193, v192
	ds_read_b128 v[198:201], v197 offset:0
	ds_read_b128 v[202:205], v223 offset:18432
	ds_read_b128 v[210:213], v197 offset:4608
	ds_read_b128 v[206:209], v223 offset:23040
	s_waitcnt lgkmcnt(2)
	v_mfma_f32_32x32x16_bf16 v[50:65], v[198:201], v[202:205], v[50:65]
	ds_read_b128 v[214:217], v197 offset:32
	s_waitcnt lgkmcnt(2)
	v_mfma_f32_32x32x16_bf16 v[2:17], v[210:213], v[202:205], v[2:17]
	ds_read_b128 v[202:205], v223 offset:18464
	s_waitcnt lgkmcnt(2)
	v_mfma_f32_32x32x16_bf16 v[18:33], v[198:201], v[206:209], v[18:33]
	ds_read_b128 v[198:201], v197 offset:4640
	v_mfma_f32_32x32x16_bf16 v[34:49], v[210:213], v[206:209], v[34:49]
	ds_read_b128 v[206:209], v223 offset:23072
	s_waitcnt lgkmcnt(2)
	v_mfma_f32_32x32x16_bf16 v[50:65], v[214:217], v[202:205], v[50:65]
	ds_read_b128 v[210:213], v197 offset:64
	s_waitcnt lgkmcnt(2)
	v_mfma_f32_32x32x16_bf16 v[2:17], v[198:201], v[202:205], v[2:17]
	ds_read_b128 v[202:205], v223 offset:18496
	s_waitcnt lgkmcnt(2)
	v_mfma_f32_32x32x16_bf16 v[18:33], v[214:217], v[206:209], v[18:33]
	ds_read_b128 v[214:217], v197 offset:4672
	v_mfma_f32_32x32x16_bf16 v[34:49], v[198:201], v[206:209], v[34:49]
	ds_read_b128 v[206:209], v223 offset:23104
	s_waitcnt lgkmcnt(2)
	v_mfma_f32_32x32x16_bf16 v[50:65], v[210:213], v[202:205], v[50:65]
	ds_read_b128 v[198:201], v197 offset:96
	s_waitcnt lgkmcnt(2)
	v_mfma_f32_32x32x16_bf16 v[2:17], v[214:217], v[202:205], v[2:17]
	ds_read_b128 v[202:205], v223 offset:18528
	s_waitcnt lgkmcnt(2)
	v_mfma_f32_32x32x16_bf16 v[18:33], v[210:213], v[206:209], v[18:33]
	ds_read_b128 v[210:213], v197 offset:4704
	v_mfma_f32_32x32x16_bf16 v[34:49], v[214:217], v[206:209], v[34:49]
	ds_read_b128 v[206:209], v223 offset:23136
	s_waitcnt lgkmcnt(2)
	v_mfma_f32_32x32x16_bf16 v[50:65], v[198:201], v[202:205], v[50:65]
	s_waitcnt lgkmcnt(1)
	v_mfma_f32_32x32x16_bf16 v[2:17], v[210:213], v[202:205], v[2:17]
	s_waitcnt lgkmcnt(0)
	v_mfma_f32_32x32x16_bf16 v[18:33], v[198:201], v[206:209], v[18:33]
	v_mfma_f32_32x32x16_bf16 v[34:49], v[210:213], v[206:209], v[34:49]
	s_setprio 0
	s_waitcnt lgkmcnt(0)
	s_barrier
	ds_write2_b32 v194, v50, v18 offset1:32
	ds_write2_b32 v194, v51, v19 offset0:132 offset1:164
	v_add_u32_e32 v18, 0x400, v194
	ds_write2_b32 v18, v52, v20 offset0:8 offset1:40
	ds_write2_b32 v18, v53, v21 offset0:140 offset1:172
	v_add_u32_e32 v18, 0x1000, v194
	ds_write2_b32 v18, v54, v22 offset0:32 offset1:64
	ds_write2_b32 v18, v55, v23 offset0:164 offset1:196
	v_add_u32_e32 v18, 0x1400, v194
	ds_write2_b32 v18, v56, v24 offset0:40 offset1:72
	ds_write2_b32 v18, v57, v25 offset0:172 offset1:204
	v_add_u32_e32 v18, 0x2000, v194
	ds_write2_b32 v18, v58, v26 offset0:64 offset1:96
	ds_write2_b32 v18, v59, v27 offset0:196 offset1:228
	v_add_u32_e32 v18, 0x2400, v194
	ds_write2_b32 v18, v60, v28 offset0:72 offset1:104
	ds_write2_b32 v18, v61, v29 offset0:204 offset1:236
	v_add_u32_e32 v18, 0x3000, v194
	ds_write2_b32 v18, v62, v30 offset0:96 offset1:128
	v_add_u32_e32 v18, 0x3200, v194
	ds_write2_b32 v18, v63, v31 offset0:100 offset1:132
	v_add_u32_e32 v18, 0x3400, v194
	ds_write2_b32 v18, v64, v32 offset0:104 offset1:136
	v_add_u32_e32 v18, 0x3600, v194
	ds_write2_b32 v18, v65, v33 offset0:108 offset1:140
	v_add_u32_e32 v18, 0x4000, v194
	ds_write2_b32 v18, v2, v34 offset0:128 offset1:160
	v_add_u32_e32 v2, 0x4400, v194
	ds_write2_b32 v2, v3, v35 offset0:4 offset1:36
	ds_write2_b32 v2, v4, v36 offset0:136 offset1:168
	v_add_u32_e32 v2, 0x4800, v194
	ds_write2_b32 v2, v5, v37 offset0:12 offset1:44
	v_add_u32_e32 v2, 0x5000, v194
	ds_write2_b32 v2, v6, v38 offset0:160 offset1:192
	v_add_u32_e32 v2, 0x5400, v194
	ds_write2_b32 v2, v7, v39 offset0:36 offset1:68
	ds_write2_b32 v2, v8, v40 offset0:168 offset1:200
	v_add_u32_e32 v2, 0x5800, v194
	ds_write2_b32 v2, v9, v41 offset0:44 offset1:76
	v_add_u32_e32 v2, 0x6000, v194
	ds_write2_b32 v2, v10, v42 offset0:192 offset1:224
	v_add_u32_e32 v2, 0x6400, v194
	ds_write2_b32 v2, v11, v43 offset0:68 offset1:100
	ds_write2_b32 v2, v12, v44 offset0:200 offset1:232
	v_add_u32_e32 v2, 0x6800, v194
	ds_write2_b32 v2, v13, v45 offset0:76 offset1:108
	v_add_u32_e32 v2, 0x7200, v194
	ds_write2_b32 v2, v14, v46 offset0:96 offset1:128
	v_add_u32_e32 v2, 0x7400, v194
	ds_write2_b32 v2, v15, v47 offset0:100 offset1:132
	v_add_u32_e32 v2, 0x7600, v194
	ds_write2_b32 v2, v16, v48 offset0:104 offset1:136
	v_add_u32_e32 v2, 0x7800, v194
	s_mov_b64 s[14:15], -1
	s_and_b64 vcc, exec, s[12:13]
	ds_write2_b32 v2, v17, v49 offset0:108 offset1:140
	s_waitcnt lgkmcnt(0)
	s_barrier
	s_cbranch_vccz .LBB0_379
	ds_read_b128 v[2:5], v195
	ds_read_b128 v[6:9], v195 offset:16
	s_waitcnt lgkmcnt(1)
	v_add_f32_e32 v10, v78, v2
	v_add_f32_e32 v11, v79, v3
	v_sub_f32_e32 v2, v78, v2
	v_sub_f32_e32 v3, v79, v3
	v_add_f32_e32 v12, v80, v4
	v_add_f32_e32 v13, v81, v5
	v_cvt_pk_bf16_f32 v2, v2, v3
	v_sub_f32_e32 v3, v80, v4
	v_sub_f32_e32 v4, v81, v5
	v_cvt_pk_bf16_f32 v10, v10, v11
	v_cvt_pk_bf16_f32 v11, v12, v13
	s_waitcnt lgkmcnt(0)
	v_add_f32_e32 v12, v74, v6
	v_add_f32_e32 v13, v75, v7
	v_cvt_pk_bf16_f32 v3, v3, v4
	v_sub_f32_e32 v4, v74, v6
	v_sub_f32_e32 v5, v75, v7
	v_cvt_pk_bf16_f32 v12, v12, v13
	v_add_f32_e32 v13, v76, v8
	v_cvt_pk_bf16_f32 v4, v4, v5
	v_sub_f32_e32 v5, v76, v8
	v_add_f32_e32 v14, v77, v9
	v_cvt_pk_bf16_f32 v13, v13, v14
	v_sub_f32_e32 v6, v77, v9
	v_cvt_pk_bf16_f32 v5, v5, v6
	global_store_dwordx4 v[148:149], v[10:13], off
	s_and_saveexec_b64 s[14:15], s[2:3]
	s_cbranch_execz .LBB0_364
	global_store_dwordx4 v[150:151], v[2:5], off

;     ...
;   for (int kt = 0; kt < nk; ++kt) {
;     const int kn = (kt + 1 < nk) ? kt + 1 : kt;
;     GM_LOAD2(kn * 64, kn * bkstep)
;     __builtin_amdgcn_sched_barrier(0);
;     const char* As = smem + (kt & 1) * 2 * TILE_B;
;     const char* Bs = As + TILE_B;
;     if constexpr (HOIST) {
;       bf16x8 fa0[4], fa1[4], fb0[4], fb1[4];
; #pragma unroll
;       for (int st = 0; st < 4; ++st) {
;         fa0[st] = *(const bf16x8*)(As + aoff + st * 32);
;         fb0[st] = *(const bf16x8*)(Bs + boff + st * 32);
;         fa1[st] = *(const bf16x8*)(As + aoff + 32 * LSTR + st * 32);
;         fb1[st] = *(const bf16x8*)(Bs + boff + 32 * LSTR + st * 32);
;       }
;       __builtin_amdgcn_sched_barrier(0);
; #pragma unroll
;       for (int st = 0; st < 4; ++st) {
;         acc[0][0] = mfma32(fa0[st], fb0[st], acc[0][0]);
;         acc[0][1] = mfma32(fa0[st], fb1[st], acc[0][1]);
;         acc[1][0] = mfma32(fa1[st], fb0[st], acc[1][0]);
;         acc[1][1] = mfma32(fa1[st], fb1[st], acc[1][1]);
;       }
;     } else {
; #pragma unroll
;       for (int st = 0; st < 4; ++st) {
;         bf16x8 a0 = *(const bf16x8*)(As + aoff + st * 32);
;         bf16x8 a1 = *(const bf16x8*)(As + aoff + 32 * LSTR + st * 32);
;         bf16x8 b0 = *(const bf16x8*)(Bs + boff + st * 32);
;         bf16x8 b1 = *(const bf16x8*)(Bs + boff + 32 * LSTR + st * 32);
;         acc[0][0] = mfma32(a0, b0, acc[0][0]);
;         acc[0][1] = mfma32(a0, b1, acc[0][1]);
;         acc[1][0] = mfma32(a1, b0, acc[1][0]);
;         acc[1][1] = mfma32(a1, b1, acc[1][1]);
;       }
;     }
;     __builtin_amdgcn_sched_barrier(0);
;     {
;       char* Ad = smem + ((kt + 1) & 1) * 2 * TILE_B;
;       GM_STORE(Ad)
;     }
;     __syncthreads();
.LBB0_632:
	s_and_b32 s38, s37, 2
	s_mulk_i32 s38, 0x4800
	v_add3_u32 v167, s38, v162, v163
	s_setprio 1
	v_add3_u32 v220, s38, v164, v163
	ds_read_b128 v[200:203], v167 offset:0
	ds_read_b128 v[204:207], v220 offset:18432
	ds_read_b128 v[212:215], v167 offset:4608
	ds_read_b128 v[208:211], v220 offset:23040
	s_waitcnt lgkmcnt(2)
	v_mfma_f32_32x32x16_bf16 v[34:49], v[200:203], v[204:207], v[34:49]
	ds_read_b128 v[216:219], v167 offset:32
	s_waitcnt lgkmcnt(2)
	v_mfma_f32_32x32x16_bf16 v[18:33], v[212:215], v[204:207], v[18:33]
	ds_read_b128 v[204:207], v220 offset:18464
	s_waitcnt lgkmcnt(2)
	v_mfma_f32_32x32x16_bf16 v[2:17], v[200:203], v[208:211], v[2:17]
	ds_read_b128 v[200:203], v167 offset:4640
	v_mfma_f32_32x32x16_bf16 v[50:65], v[212:215], v[208:211], v[50:65]
	ds_read_b128 v[208:211], v220 offset:23072
	s_waitcnt lgkmcnt(2)
	v_mfma_f32_32x32x16_bf16 v[34:49], v[216:219], v[204:207], v[34:49]
	ds_read_b128 v[212:215], v167 offset:64
	s_waitcnt lgkmcnt(2)
	v_mfma_f32_32x32x16_bf16 v[18:33], v[200:203], v[204:207], v[18:33]
	ds_read_b128 v[204:207], v220 offset:18496
	s_waitcnt lgkmcnt(2)
	v_mfma_f32_32x32x16_bf16 v[2:17], v[216:219], v[208:211], v[2:17]
	ds_read_b128 v[216:219], v167 offset:4672
	v_mfma_f32_32x32x16_bf16 v[50:65], v[200:203], v[208:211], v[50:65]
	ds_read_b128 v[208:211], v220 offset:23104
	s_waitcnt lgkmcnt(2)
	v_mfma_f32_32x32x16_bf16 v[34:49], v[212:215], v[204:207], v[34:49]
	ds_read_b128 v[200:203], v167 offset:96
	s_waitcnt lgkmcnt(2)
	v_mfma_f32_32x32x16_bf16 v[18:33], v[216:219], v[204:207], v[18:33]
	ds_read_b128 v[204:207], v220 offset:18528
	s_waitcnt lgkmcnt(2)
	v_mfma_f32_32x32x16_bf16 v[2:17], v[212:215], v[208:211], v[2:17]
	ds_read_b128 v[212:215], v167 offset:4704
	v_mfma_f32_32x32x16_bf16 v[50:65], v[216:219], v[208:211], v[50:65]
	ds_read_b128 v[208:211], v220 offset:23136
	s_waitcnt lgkmcnt(2)
	v_mfma_f32_32x32x16_bf16 v[34:49], v[200:203], v[204:207], v[34:49]
	s_waitcnt lgkmcnt(1)
	v_mfma_f32_32x32x16_bf16 v[18:33], v[212:215], v[204:207], v[18:33]
	s_waitcnt lgkmcnt(0)
	v_mfma_f32_32x32x16_bf16 v[2:17], v[200:203], v[208:211], v[2:17]
	v_mfma_f32_32x32x16_bf16 v[50:65], v[212:215], v[208:211], v[50:65]
	s_setprio 0
	s_add_i32 s37, s37, 2
	s_and_b32 s38, s37, 2
	s_mulk_i32 s38, 0x4800
	s_add_i32 s6, s6, -1
	v_add_u32_e32 v167, s38, v135
	v_lshl_add_u64 v[146:147], v[146:147], 0, s[8:9]
	v_lshl_add_u64 v[148:149], v[148:149], 0, s[8:9]
	v_lshl_add_u64 v[150:151], v[150:151], 0, s[8:9]
	v_lshl_add_u64 v[152:153], v[152:153], 0, s[8:9]
	v_lshl_add_u64 v[154:155], v[154:155], 0, s[8:9]
	v_lshl_add_u64 v[156:157], v[156:157], 0, s[8:9]
	v_lshl_add_u64 v[158:159], v[158:159], 0, s[8:9]
	v_lshl_add_u64 v[160:161], v[160:161], 0, s[8:9]
	s_cmp_lg_u32 s6, 0
	s_waitcnt vmcnt(7)
	ds_write_b128 v167, v[168:171]
	v_lshl_add_u64 v[168:169], v[146:147], 0, v[68:69]
	global_load_dwordx4 v[168:171], v[168:169], off offset:128
	s_waitcnt vmcnt(7)
	ds_write_b128 v167, v[172:175] offset:4608
	v_lshl_add_u64 v[172:173], v[148:149], 0, v[68:69]
	global_load_dwordx4 v[172:175], v[172:173], off offset:128
	s_waitcnt vmcnt(7)
	ds_write_b128 v167, v[176:179] offset:9216
	v_lshl_add_u64 v[176:177], v[150:151], 0, v[68:69]
	global_load_dwordx4 v[176:179], v[176:177], off offset:128
	s_waitcnt vmcnt(7)
	ds_write_b128 v167, v[180:183] offset:13824
	v_lshl_add_u64 v[180:181], v[152:153], 0, v[68:69]
	global_load_dwordx4 v[180:183], v[180:181], off offset:128
	s_waitcnt vmcnt(7)
	ds_write_b128 v167, v[184:187] offset:18432
	v_lshl_add_u64 v[184:185], v[154:155], 0, v[68:69]
	global_load_dwordx4 v[184:187], v[184:185], off offset:128
	s_waitcnt vmcnt(7)
	ds_write_b128 v167, v[188:191] offset:23040
	v_lshl_add_u64 v[188:189], v[156:157], 0, v[68:69]
	global_load_dwordx4 v[188:191], v[188:189], off offset:128
	s_waitcnt vmcnt(7)
	ds_write_b128 v167, v[192:195] offset:27648
	v_lshl_add_u64 v[192:193], v[158:159], 0, v[68:69]
	global_load_dwordx4 v[192:195], v[192:193], off offset:128
	s_waitcnt vmcnt(7)
	ds_write_b128 v167, v[196:199] offset:32256
	v_lshl_add_u64 v[196:197], v[160:161], 0, v[68:69]
	global_load_dwordx4 v[196:199], v[196:197], off offset:128
	s_waitcnt lgkmcnt(0)
	s_barrier
	s_cbranch_scc1 .LBB0_632
	s_and_b32 s38, s37, 2
	s_mulk_i32 s38, 0x4800
	v_add3_u32 v167, s38, v162, v163
	s_setprio 1
	v_add3_u32 v220, s38, v164, v163
	ds_read_b128 v[200:203], v167 offset:0
	ds_read_b128 v[204:207], v220 offset:18432
	ds_read_b128 v[212:215], v167 offset:4608
	ds_read_b128 v[208:211], v220 offset:23040
	s_waitcnt lgkmcnt(2)
	v_mfma_f32_32x32x16_bf16 v[34:49], v[200:203], v[204:207], v[34:49]
	ds_read_b128 v[216:219], v167 offset:32
	s_waitcnt lgkmcnt(2)
	v_mfma_f32_32x32x16_bf16 v[18:33], v[212:215], v[204:207], v[18:33]
	ds_read_b128 v[204:207], v220 offset:18464
	s_waitcnt lgkmcnt(2)
	v_mfma_f32_32x32x16_bf16 v[2:17], v[200:203], v[208:211], v[2:17]
	ds_read_b128 v[200:203], v167 offset:4640
	v_mfma_f32_32x32x16_bf16 v[50:65], v[212:215], v[208:211], v[50:65]
	ds_read_b128 v[208:211], v220 offset:23072
	s_waitcnt lgkmcnt(2)
	v_mfma_f32_32x32x16_bf16 v[34:49], v[216:219], v[204:207], v[34:49]
	ds_read_b128 v[212:215], v167 offset:64
	s_waitcnt lgkmcnt(2)
	v_mfma_f32_32x32x16_bf16 v[18:33], v[200:203], v[204:207], v[18:33]
	ds_read_b128 v[204:207], v220 offset:18496
	s_waitcnt lgkmcnt(2)
	v_mfma_f32_32x32x16_bf16 v[2:17], v[216:219], v[208:211], v[2:17]
	ds_read_b128 v[216:219], v167 offset:4672
	v_mfma_f32_32x32x16_bf16 v[50:65], v[200:203], v[208:211], v[50:65]
	ds_read_b128 v[208:211], v220 offset:23104
	s_waitcnt lgkmcnt(2)
	v_mfma_f32_32x32x16_bf16 v[34:49], v[212:215], v[204:207], v[34:49]
	ds_read_b128 v[200:203], v167 offset:96
	s_waitcnt lgkmcnt(2)
;     ...
;         acc[0][0] = mfma32(fa0[st], fb0[st], acc[0][0]);
;         acc[0][1] = mfma32(fa0[st], fb1[st], acc[0][1]);
;         acc[1][0] = mfma32(fa1[st], fb0[st], acc[1][0]);
;         acc[1][1] = mfma32(fa1[st], fb1[st], acc[1][1]);
;       }
;     } else {
; #pragma unroll
;       for (int st = 0; st < 4; ++st) {
;         bf16x8 a0 = *(const bf16x8*)(As + aoff + st * 32);
;         bf16x8 a1 = *(const bf16x8*)(As + aoff + 32 * LSTR + st * 32);
;         bf16x8 b0 = *(const bf16x8*)(Bs + boff + st * 32);
;         bf16x8 b1 = *(const bf16x8*)(Bs + boff + 32 * LSTR + st * 32);
;         acc[0][0] = mfma32(a0, b0, acc[0][0]);
;         acc[0][1] = mfma32(a0, b1, acc[0][1]);
;         acc[1][0] = mfma32(a1, b0, acc[1][0]);
;         acc[1][1] = mfma32(a1, b1, acc[1][1]);
;       }
;     }
;     __builtin_amdgcn_sched_barrier(0);
;     {
;       char* Ad = smem + ((kt + 1) & 1) * 2 * TILE_B;
;       GM_STORE(Ad)
;     }
;     __syncthreads();
; __device__ __forceinline__ void acc_to_lds(const f32x16 (&acc)[2][2], float* cs) {
;     ...
;       for (int r = 0; r < 16; ++r) {
;         int row = wm * 64 + i * 32 + (r & 3) + 8 * (r >> 2) + 4 * (lane >> 5);
;         int col = wn * 64 + j * 32 + (lane & 31);
;         cs[row * CSTR + col] = acc[i][j][r];
;       }
;   __syncthreads();
; __device__ __forceinline__ void merge_tile(const Params& P, int l, int mt, int nt, char* smem) {
;     ...
;     const u16* gp = WSP(u16, OFF_G) + grow * 3072 + br * 1024 + nt * 128 + half * 64;
	v_mfma_f32_32x32x16_bf16 v[18:33], v[216:219], v[204:207], v[18:33]
	ds_read_b128 v[204:207], v220 offset:18528
	s_waitcnt lgkmcnt(2)
	v_mfma_f32_32x32x16_bf16 v[2:17], v[212:215], v[208:211], v[2:17]
	ds_read_b128 v[212:215], v167 offset:4704
	v_mfma_f32_32x32x16_bf16 v[50:65], v[216:219], v[208:211], v[50:65]
	ds_read_b128 v[208:211], v220 offset:23136
	s_waitcnt lgkmcnt(2)
	v_mfma_f32_32x32x16_bf16 v[34:49], v[200:203], v[204:207], v[34:49]
	s_waitcnt lgkmcnt(1)
	v_mfma_f32_32x32x16_bf16 v[18:33], v[212:215], v[204:207], v[18:33]
	s_waitcnt lgkmcnt(0)
	v_mfma_f32_32x32x16_bf16 v[2:17], v[200:203], v[208:211], v[2:17]
	v_mfma_f32_32x32x16_bf16 v[50:65], v[212:215], v[208:211], v[50:65]
	s_setprio 0
	s_add_i32 s37, s37, 2
	s_and_b32 s38, s37, 2
	s_mulk_i32 s38, 0x4800
	v_add_u32_e32 v167, s38, v135
	v_lshl_add_u64 v[146:147], v[146:147], 0, s[8:9]
	v_lshl_add_u64 v[148:149], v[148:149], 0, s[8:9]
	v_lshl_add_u64 v[150:151], v[150:151], 0, s[8:9]
	v_lshl_add_u64 v[152:153], v[152:153], 0, s[8:9]
	v_lshl_add_u64 v[154:155], v[154:155], 0, s[8:9]
	v_lshl_add_u64 v[156:157], v[156:157], 0, s[8:9]
	v_lshl_add_u64 v[158:159], v[158:159], 0, s[8:9]
	v_lshl_add_u64 v[160:161], v[160:161], 0, s[8:9]
	s_waitcnt vmcnt(7)
	ds_write_b128 v167, v[168:171]
	s_waitcnt vmcnt(6)
	ds_write_b128 v167, v[172:175] offset:4608
	s_waitcnt vmcnt(5)
	ds_write_b128 v167, v[176:179] offset:9216
	s_waitcnt vmcnt(4)
	ds_write_b128 v167, v[180:183] offset:13824
	s_waitcnt vmcnt(3)
	ds_write_b128 v167, v[184:187] offset:18432
	s_waitcnt vmcnt(2)
	ds_write_b128 v167, v[188:191] offset:23040
	s_waitcnt vmcnt(1)
	ds_write_b128 v167, v[192:195] offset:27648
	s_waitcnt vmcnt(0)
	ds_write_b128 v167, v[196:199] offset:32256
	s_waitcnt lgkmcnt(0)
	s_barrier
	v_lshl_add_u64 v[180:181], v[160:161], 0, v[68:69]
	v_lshl_add_u64 v[176:177], v[158:159], 0, v[68:69]
	v_lshl_add_u64 v[172:173], v[156:157], 0, v[68:69]
	v_lshl_add_u64 v[168:169], v[154:155], 0, v[68:69]
	v_lshl_add_u64 v[158:159], v[152:153], 0, v[68:69]
	v_lshl_add_u64 v[154:155], v[150:151], 0, v[68:69]
	v_lshl_add_u64 v[150:151], v[148:149], 0, v[68:69]
	v_lshl_add_u64 v[146:147], v[146:147], 0, v[68:69]
	s_nop 0
	s_nop 0
	s_nop 0
	s_nop 0
	s_nop 0
	s_nop 0
	s_nop 0
	v_add3_u32 v68, s38, v162, v163
	s_setprio 1
	v_add3_u32 v167, s38, v164, v163
	ds_read_b128 v[184:187], v68 offset:0
	ds_read_b128 v[188:191], v167 offset:18432
	ds_read_b128 v[196:199], v68 offset:4608
	ds_read_b128 v[192:195], v167 offset:23040
	s_waitcnt lgkmcnt(2)
	v_mfma_f32_32x32x16_bf16 v[34:49], v[184:187], v[188:191], v[34:49]
	ds_read_b128 v[200:203], v68 offset:32
	s_waitcnt lgkmcnt(2)
	v_mfma_f32_32x32x16_bf16 v[18:33], v[196:199], v[188:191], v[18:33]
	ds_read_b128 v[188:191], v167 offset:18464
	s_waitcnt lgkmcnt(2)
	v_mfma_f32_32x32x16_bf16 v[2:17], v[184:187], v[192:195], v[2:17]
	ds_read_b128 v[184:187], v68 offset:4640
	v_mfma_f32_32x32x16_bf16 v[50:65], v[196:199], v[192:195], v[50:65]
	ds_read_b128 v[192:195], v167 offset:23072
	s_waitcnt lgkmcnt(2)
	v_mfma_f32_32x32x16_bf16 v[34:49], v[200:203], v[188:191], v[34:49]
	ds_read_b128 v[196:199], v68 offset:64
	s_waitcnt lgkmcnt(2)
	v_mfma_f32_32x32x16_bf16 v[18:33], v[184:187], v[188:191], v[18:33]
	ds_read_b128 v[188:191], v167 offset:18496
	s_waitcnt lgkmcnt(2)
	v_mfma_f32_32x32x16_bf16 v[2:17], v[200:203], v[192:195], v[2:17]
	ds_read_b128 v[200:203], v68 offset:4672
	v_mfma_f32_32x32x16_bf16 v[50:65], v[184:187], v[192:195], v[50:65]
	ds_read_b128 v[192:195], v167 offset:23104
	s_waitcnt lgkmcnt(2)
	v_mfma_f32_32x32x16_bf16 v[34:49], v[196:199], v[188:191], v[34:49]
	ds_read_b128 v[184:187], v68 offset:96
	s_waitcnt lgkmcnt(2)
	v_mfma_f32_32x32x16_bf16 v[18:33], v[200:203], v[188:191], v[18:33]
	ds_read_b128 v[188:191], v167 offset:18528
	s_waitcnt lgkmcnt(2)
	v_mfma_f32_32x32x16_bf16 v[2:17], v[196:199], v[192:195], v[2:17]
	ds_read_b128 v[196:199], v68 offset:4704
	v_mfma_f32_32x32x16_bf16 v[50:65], v[200:203], v[192:195], v[50:65]
	ds_read_b128 v[192:195], v167 offset:23136
	s_waitcnt lgkmcnt(2)
	v_mfma_f32_32x32x16_bf16 v[34:49], v[184:187], v[188:191], v[34:49]
	s_waitcnt lgkmcnt(1)
	v_mfma_f32_32x32x16_bf16 v[18:33], v[196:199], v[188:191], v[18:33]
	s_waitcnt lgkmcnt(0)
	v_mfma_f32_32x32x16_bf16 v[2:17], v[184:187], v[192:195], v[2:17]
	v_mfma_f32_32x32x16_bf16 v[50:65], v[196:199], v[192:195], v[50:65]
	s_setprio 0
	s_waitcnt lgkmcnt(0)
	s_barrier
	ds_write2_b32 v165, v34, v2 offset1:32
	ds_write2_b32 v165, v35, v3 offset0:132 offset1:164
	v_add_u32_e32 v2, 0x400, v165
	ds_write2_b32 v2, v36, v4 offset0:8 offset1:40
	ds_write2_b32 v2, v37, v5 offset0:140 offset1:172
	v_add_u32_e32 v2, 0x1000, v165
	ds_write2_b32 v2, v38, v6 offset0:32 offset1:64
	ds_write2_b32 v2, v39, v7 offset0:164 offset1:196
	v_add_u32_e32 v2, 0x1400, v165
	ds_write2_b32 v2, v40, v8 offset0:40 offset1:72
	ds_write2_b32 v2, v41, v9 offset0:172 offset1:204
	v_add_u32_e32 v2, 0x2000, v165
	ds_write2_b32 v2, v42, v10 offset0:64 offset1:96
	ds_write2_b32 v2, v43, v11 offset0:196 offset1:228
	v_add_u32_e32 v2, 0x2400, v165
	ds_write2_b32 v2, v44, v12 offset0:72 offset1:104
	ds_write2_b32 v2, v45, v13 offset0:204 offset1:236
	v_add_u32_e32 v2, 0x3000, v165
	ds_write2_b32 v2, v46, v14 offset0:96 offset1:128
	v_add_u32_e32 v2, 0x3200, v165
	ds_write2_b32 v2, v47, v15 offset0:100 offset1:132
	v_add_u32_e32 v2, 0x3400, v165
	ds_write2_b32 v2, v48, v16 offset0:104 offset1:136
	v_add_u32_e32 v2, 0x3600, v165
	ds_write2_b32 v2, v49, v17 offset0:108 offset1:140
	v_add_u32_e32 v2, 0x4000, v165
	ds_write2_b32 v2, v18, v50 offset0:128 offset1:160
	v_add_u32_e32 v2, 0x4400, v165
	ds_write2_b32 v2, v19, v51 offset0:4 offset1:36
	ds_write2_b32 v2, v20, v52 offset0:136 offset1:168
	v_add_u32_e32 v2, 0x4800, v165
	ds_write2_b32 v2, v21, v53 offset0:12 offset1:44
	v_add_u32_e32 v2, 0x5000, v165
	ds_write2_b32 v2, v22, v54 offset0:160 offset1:192
	v_add_u32_e32 v2, 0x5400, v165
	ds_write2_b32 v2, v23, v55 offset0:36 offset1:68
	ds_write2_b32 v2, v24, v56 offset0:168 offset1:200
	v_add_u32_e32 v2, 0x5800, v165
	ds_write2_b32 v2, v25, v57 offset0:44 offset1:76
	v_add_u32_e32 v2, 0x6000, v165
	ds_write2_b32 v2, v26, v58 offset0:192 offset1:224
	v_add_u32_e32 v2, 0x6400, v165
	ds_write2_b32 v2, v27, v59 offset0:68 offset1:100
	ds_write2_b32 v2, v28, v60 offset0:200 offset1:232
	v_add_u32_e32 v2, 0x6800, v165
	ds_write2_b32 v2, v29, v61 offset0:76 offset1:108
	v_add_u32_e32 v2, 0x7200, v165
	ds_write2_b32 v2, v30, v62 offset0:96 offset1:128
	v_add_u32_e32 v2, 0x7400, v165
	ds_write2_b32 v2, v31, v63 offset0:100 offset1:132
	v_add_u32_e32 v2, 0x7600, v165
	s_lshl_b32 s6, s36, 11
	ds_write2_b32 v2, v32, v64 offset0:104 offset1:136
	v_add_u32_e32 v2, 0x7800, v165
	v_lshl_add_u64 v[46:47], v[116:117], 0, s[6:7]
	ds_write2_b32 v2, v33, v65 offset0:108 offset1:140
	s_waitcnt lgkmcnt(0)
	s_barrier
; __device__ __forceinline__ void merge_tile(const Params& P, int l, int mt, int nt, char* smem) {
;     ...
;     const u16* gp = WSP(u16, OFF_G) + grow * 3072 + br * 1024 + nt * 128 + half * 64;
; #pragma unroll
;     for (int q = 0; q < 8; ++q) {
;       uint4 gq = *(const uint4*)(gp + q * 8);
;       float4 a = *(const float4*)(cs + r * CSTR + half * 64 + q * 8);
;       float4 c = *(const float4*)(cs + r * CSTR + half * 64 + q * 8 + 4);
;       macc[q * 8 + 0] += __uint_as_float(gq.x << 16) * a.x;
;       macc[q * 8 + 1] += __uint_as_float(gq.x & 0xffff0000u) * a.y;
;       macc[q * 8 + 2] += __uint_as_float(gq.y << 16) * a.z;
;       macc[q * 8 + 3] += __uint_as_float(gq.y & 0xffff0000u) * a.w;
;       macc[q * 8 + 4] += __uint_as_float(gq.z << 16) * c.x;
;       macc[q * 8 + 5] += __uint_as_float(gq.z & 0xffff0000u) * c.y;
;       macc[q * 8 + 6] += __uint_as_float(gq.w << 16) * c.z;
;       macc[q * 8 + 7] += __uint_as_float(gq.w & 0xffff0000u) * c.w;
;     }
;     __syncthreads();
	global_load_dwordx4 v[2:5], v[46:47], off
	global_load_dwordx4 v[6:9], v[46:47], off offset:16
	global_load_dwordx4 v[10:13], v[46:47], off offset:32
	global_load_dwordx4 v[14:17], v[46:47], off offset:48
	global_load_dwordx4 v[18:21], v[46:47], off offset:64
	global_load_dwordx4 v[22:25], v[46:47], off offset:80
	ds_read_b128 v[26:29], v166
	ds_read_b128 v[30:33], v166 offset:16
	ds_read_b128 v[34:37], v166 offset:32
	ds_read_b128 v[38:41], v166 offset:48
	global_load_dwordx4 v[42:45], v[46:47], off offset:112
	s_nop 0
	global_load_dwordx4 v[46:49], v[46:47], off offset:96
	s_add_i32 s36, s36, 1
	s_cmp_lg_u32 s36, 3
	s_waitcnt vmcnt(7)
	v_lshlrev_b32_e32 v50, 16, v2
	v_and_b32_e32 v51, 0xffff0000, v2
	v_lshlrev_b32_e32 v2, 16, v3
	v_and_b32_e32 v3, 0xffff0000, v3
	s_waitcnt lgkmcnt(3)
	v_pk_fma_f32 v[142:143], v[28:29], v[2:3], v[142:143]
	v_lshlrev_b32_e32 v2, 16, v4
	v_and_b32_e32 v3, 0xffff0000, v4
	s_waitcnt lgkmcnt(2)
	v_pk_fma_f32 v[140:141], v[30:31], v[2:3], v[140:141]
	v_lshlrev_b32_e32 v2, 16, v5
	v_and_b32_e32 v3, 0xffff0000, v5
	v_pk_fma_f32 v[138:139], v[32:33], v[2:3], v[138:139]
	s_waitcnt vmcnt(6)
	v_lshlrev_b32_e32 v2, 16, v6
	v_and_b32_e32 v3, 0xffff0000, v6
	s_waitcnt lgkmcnt(1)
	v_pk_fma_f32 v[136:137], v[34:35], v[2:3], v[136:137]
	v_lshlrev_b32_e32 v2, 16, v7
	v_and_b32_e32 v3, 0xffff0000, v7
	v_pk_fma_f32 v[132:133], v[36:37], v[2:3], v[132:133]
	v_lshlrev_b32_e32 v2, 16, v8
	v_and_b32_e32 v3, 0xffff0000, v8
	s_waitcnt lgkmcnt(0)
	v_pk_fma_f32 v[130:131], v[38:39], v[2:3], v[130:131]
	ds_read_b128 v[2:5], v166 offset:64
	v_lshlrev_b32_e32 v6, 16, v9
	v_and_b32_e32 v7, 0xffff0000, v9
	v_pk_fma_f32 v[128:129], v[40:41], v[6:7], v[128:129]
	ds_read_b128 v[6:9], v166 offset:80
	v_pk_fma_f32 v[144:145], v[26:27], v[50:51], v[144:145]
	s_waitcnt vmcnt(5)
	v_lshlrev_b32_e32 v26, 16, v10
	v_and_b32_e32 v27, 0xffff0000, v10
	s_waitcnt lgkmcnt(1)
	v_pk_fma_f32 v[126:127], v[2:3], v[26:27], v[126:127]
	v_lshlrev_b32_e32 v2, 16, v11
	v_and_b32_e32 v3, 0xffff0000, v11
	v_pk_fma_f32 v[124:125], v[4:5], v[2:3], v[124:125]
	v_lshlrev_b32_e32 v2, 16, v12
	v_and_b32_e32 v3, 0xffff0000, v12
	s_waitcnt lgkmcnt(0)
	v_pk_fma_f32 v[122:123], v[6:7], v[2:3], v[122:123]
	ds_read_b128 v[2:5], v166 offset:96
	v_lshlrev_b32_e32 v6, 16, v13
	v_and_b32_e32 v7, 0xffff0000, v13
	v_pk_fma_f32 v[120:121], v[8:9], v[6:7], v[120:121]
	ds_read_b128 v[6:9], v166 offset:112
	s_waitcnt vmcnt(4)
	v_lshlrev_b32_e32 v10, 16, v14
	v_and_b32_e32 v11, 0xffff0000, v14
	s_waitcnt lgkmcnt(1)
	v_pk_fma_f32 v[118:119], v[2:3], v[10:11], v[118:119]
	v_lshlrev_b32_e32 v2, 16, v15
	v_and_b32_e32 v3, 0xffff0000, v15
	v_pk_fma_f32 v[114:115], v[4:5], v[2:3], v[114:115]
	v_lshlrev_b32_e32 v2, 16, v16
	v_and_b32_e32 v3, 0xffff0000, v16
	s_waitcnt lgkmcnt(0)
	v_pk_fma_f32 v[112:113], v[6:7], v[2:3], v[112:113]
	ds_read_b128 v[2:5], v166 offset:128
	v_lshlrev_b32_e32 v6, 16, v17
	v_and_b32_e32 v7, 0xffff0000, v17
	v_pk_fma_f32 v[110:111], v[8:9], v[6:7], v[110:111]
	ds_read_b128 v[6:9], v166 offset:144
	s_waitcnt vmcnt(3)
	v_lshlrev_b32_e32 v10, 16, v18
	v_and_b32_e32 v11, 0xffff0000, v18
	s_waitcnt lgkmcnt(1)
	v_pk_fma_f32 v[106:107], v[2:3], v[10:11], v[106:107]
	v_lshlrev_b32_e32 v2, 16, v19
	v_and_b32_e32 v3, 0xffff0000, v19
	v_pk_fma_f32 v[104:105], v[4:5], v[2:3], v[104:105]
	v_lshlrev_b32_e32 v2, 16, v20
	v_and_b32_e32 v3, 0xffff0000, v20
	s_waitcnt lgkmcnt(0)
	v_pk_fma_f32 v[102:103], v[6:7], v[2:3], v[102:103]
	ds_read_b128 v[2:5], v166 offset:160
	v_lshlrev_b32_e32 v6, 16, v21
	v_and_b32_e32 v7, 0xffff0000, v21
	v_pk_fma_f32 v[100:101], v[8:9], v[6:7], v[100:101]
	ds_read_b128 v[6:9], v166 offset:176
	s_waitcnt vmcnt(2)
	v_lshlrev_b32_e32 v10, 16, v22
	v_and_b32_e32 v11, 0xffff0000, v22
	s_waitcnt lgkmcnt(1)
	v_pk_fma_f32 v[98:99], v[2:3], v[10:11], v[98:99]
	v_lshlrev_b32_e32 v2, 16, v23
	v_and_b32_e32 v3, 0xffff0000, v23
	v_pk_fma_f32 v[96:97], v[4:5], v[2:3], v[96:97]
	v_lshlrev_b32_e32 v2, 16, v24
	v_and_b32_e32 v3, 0xffff0000, v24
	s_waitcnt lgkmcnt(0)
	v_pk_fma_f32 v[94:95], v[6:7], v[2:3], v[94:95]
	ds_read_b128 v[2:5], v166 offset:192
	v_lshlrev_b32_e32 v6, 16, v25
	v_and_b32_e32 v7, 0xffff0000, v25
	v_pk_fma_f32 v[92:93], v[8:9], v[6:7], v[92:93]
	ds_read_b128 v[6:9], v166 offset:208
	s_waitcnt vmcnt(0)
	v_lshlrev_b32_e32 v10, 16, v46
	v_and_b32_e32 v11, 0xffff0000, v46
	s_waitcnt lgkmcnt(1)
	v_pk_fma_f32 v[90:91], v[2:3], v[10:11], v[90:91]
	v_lshlrev_b32_e32 v2, 16, v47
	v_and_b32_e32 v3, 0xffff0000, v47
	v_pk_fma_f32 v[88:89], v[4:5], v[2:3], v[88:89]
	v_lshlrev_b32_e32 v2, 16, v48
	v_and_b32_e32 v3, 0xffff0000, v48
	s_waitcnt lgkmcnt(0)
	v_pk_fma_f32 v[86:87], v[6:7], v[2:3], v[86:87]
	ds_read_b128 v[2:5], v166 offset:224
	v_lshlrev_b32_e32 v6, 16, v49
	v_and_b32_e32 v7, 0xffff0000, v49
	v_pk_fma_f32 v[84:85], v[8:9], v[6:7], v[84:85]
	ds_read_b128 v[6:9], v166 offset:240
	v_lshlrev_b32_e32 v10, 16, v42
	v_and_b32_e32 v11, 0xffff0000, v42
	s_waitcnt lgkmcnt(1)
	v_pk_fma_f32 v[82:83], v[2:3], v[10:11], v[82:83]
	v_lshlrev_b32_e32 v2, 16, v43
	v_and_b32_e32 v3, 0xffff0000, v43
	v_pk_fma_f32 v[80:81], v[4:5], v[2:3], v[80:81]
	v_lshlrev_b32_e32 v2, 16, v44
	v_and_b32_e32 v3, 0xffff0000, v44
	s_waitcnt lgkmcnt(0)
	v_pk_fma_f32 v[78:79], v[6:7], v[2:3], v[78:79]
	v_lshlrev_b32_e32 v2, 16, v45
	v_and_b32_e32 v3, 0xffff0000, v45
	v_pk_fma_f32 v[76:77], v[8:9], v[2:3], v[76:77]
	s_barrier
; __device__ __forceinline__ void store_row64_bf16(const float* v, u16* dst) {
; #pragma unroll
;   for (int q = 0; q < 8; ++q) {
;     uint4 o;
;     o.x = pack2(v[q * 8 + 0], v[q * 8 + 1]);
;     o.y = pack2(v[q * 8 + 2], v[q * 8 + 3]);
;     o.z = pack2(v[q * 8 + 4], v[q * 8 + 5]);
;     o.w = pack2(v[q * 8 + 6], v[q * 8 + 7]);
;     *(uint4*)(dst + q * 8) = o;
;   }
; __device__ __forceinline__ void merge_tile(const Params& P, int l, int mt, int nt, char* smem) {
;     ...
;   store_row64_bf16(macc, WSP(u16, OFF_M) + grow * DM + nt * 128 + half * 64);
	s_cbranch_scc1 .LBB0_631
	v_lshlrev_b64 v[2:3], 11, v[108:109]
	v_lshl_add_u64 v[2:3], s[4:5], 0, v[2:3]
	v_lshl_add_u64 v[2:3], s[12:13], 1, v[2:3]
	v_mov_b32_e32 v75, v69
	v_lshl_add_u64 v[6:7], v[2:3], 0, v[74:75]
	v_cvt_pk_bf16_f32 v2, v144, v145
	v_cvt_pk_bf16_f32 v3, v142, v143
	v_cvt_pk_bf16_f32 v4, v140, v141
	v_cvt_pk_bf16_f32 v5, v138, v139
	global_store_dwordx4 v[6:7], v[2:5], off
	v_readlane_b32 s40, v253, 37
	v_readlane_b32 s48, v253, 45
	v_cvt_pk_bf16_f32 v2, v136, v137
	v_cvt_pk_bf16_f32 v3, v132, v133
	v_cvt_pk_bf16_f32 v4, v130, v131
	v_cvt_pk_bf16_f32 v5, v128, v129
	global_store_dwordx4 v[6:7], v[2:5], off offset:16
	v_readlane_b32 s49, v253, 46
	v_readlane_b32 s50, v253, 47
	v_cvt_pk_bf16_f32 v2, v126, v127
	v_cvt_pk_bf16_f32 v3, v124, v125
	v_cvt_pk_bf16_f32 v4, v122, v123
	v_cvt_pk_bf16_f32 v5, v120, v121
	global_store_dwordx4 v[6:7], v[2:5], off offset:32
	v_readlane_b32 s51, v253, 48
	v_readlane_b32 s52, v253, 49
	v_cvt_pk_bf16_f32 v2, v118, v119
	v_cvt_pk_bf16_f32 v3, v114, v115
	v_cvt_pk_bf16_f32 v4, v112, v113
	v_cvt_pk_bf16_f32 v5, v110, v111
	global_store_dwordx4 v[6:7], v[2:5], off offset:48
	v_readlane_b32 s53, v253, 50
	v_readlane_b32 s54, v253, 51
	v_cvt_pk_bf16_f32 v2, v106, v107
	v_cvt_pk_bf16_f32 v3, v104, v105
	v_cvt_pk_bf16_f32 v4, v102, v103
	v_cvt_pk_bf16_f32 v5, v100, v101
	global_store_dwordx4 v[6:7], v[2:5], off offset:64
	v_readlane_b32 s55, v253, 52
	v_readlane_b32 s41, v253, 38
	v_cvt_pk_bf16_f32 v2, v98, v99
	v_cvt_pk_bf16_f32 v3, v96, v97
	v_cvt_pk_bf16_f32 v4, v94, v95
	v_cvt_pk_bf16_f32 v5, v92, v93
	global_store_dwordx4 v[6:7], v[2:5], off offset:80
	v_readlane_b32 s42, v253, 39
	v_readlane_b32 s43, v253, 40
	v_cvt_pk_bf16_f32 v2, v90, v91
	v_cvt_pk_bf16_f32 v3, v88, v89
	v_cvt_pk_bf16_f32 v4, v86, v87
	v_cvt_pk_bf16_f32 v5, v84, v85
	global_store_dwordx4 v[6:7], v[2:5], off offset:96
	v_readlane_b32 s44, v253, 41
	v_readlane_b32 s45, v253, 42
	v_cvt_pk_bf16_f32 v2, v82, v83
	v_cvt_pk_bf16_f32 v3, v80, v81
	v_cvt_pk_bf16_f32 v4, v78, v79
	v_cvt_pk_bf16_f32 v5, v76, v77
	global_store_dwordx4 v[6:7], v[2:5], off offset:112
	v_readlane_b32 s46, v253, 43
	v_readlane_b32 s47, v253, 44
	s_branch .LBB0_628

;     ...
;   for (int kt = 0; kt < nk; ++kt) {
;     const int kn = (kt + 1 < nk) ? kt + 1 : kt;
;     GM_LOAD2(kn * 64, kn * bkstep)
;     __builtin_amdgcn_sched_barrier(0);
;     const char* As = smem + (kt & 1) * 2 * TILE_B;
;     const char* Bs = As + TILE_B;
;     if constexpr (HOIST) {
;       bf16x8 fa0[4], fa1[4], fb0[4], fb1[4];
; #pragma unroll
;       for (int st = 0; st < 4; ++st) {
;         fa0[st] = *(const bf16x8*)(As + aoff + st * 32);
;         fb0[st] = *(const bf16x8*)(Bs + boff + st * 32);
;         fa1[st] = *(const bf16x8*)(As + aoff + 32 * LSTR + st * 32);
;         fb1[st] = *(const bf16x8*)(Bs + boff + 32 * LSTR + st * 32);
;       }
;       __builtin_amdgcn_sched_barrier(0);
; #pragma unroll
;       for (int st = 0; st < 4; ++st) {
;         acc[0][0] = mfma32(fa0[st], fb0[st], acc[0][0]);
;         acc[0][1] = mfma32(fa0[st], fb1[st], acc[0][1]);
;         acc[1][0] = mfma32(fa1[st], fb0[st], acc[1][0]);
;         acc[1][1] = mfma32(fa1[st], fb1[st], acc[1][1]);
;       }
;     } else {
; #pragma unroll
;       for (int st = 0; st < 4; ++st) {
;         bf16x8 a0 = *(const bf16x8*)(As + aoff + st * 32);
;         bf16x8 a1 = *(const bf16x8*)(As + aoff + 32 * LSTR + st * 32);
;         bf16x8 b0 = *(const bf16x8*)(Bs + boff + st * 32);
;         bf16x8 b1 = *(const bf16x8*)(Bs + boff + 32 * LSTR + st * 32);
;         acc[0][0] = mfma32(a0, b0, acc[0][0]);
;         acc[0][1] = mfma32(a0, b1, acc[0][1]);
;         acc[1][0] = mfma32(a1, b0, acc[1][0]);
;         acc[1][1] = mfma32(a1, b1, acc[1][1]);
;       }
;     }
;     __builtin_amdgcn_sched_barrier(0);
;     {
;       char* Ad = smem + ((kt + 1) & 1) * 2 * TILE_B;
;       GM_STORE(Ad)
;     }
;     __syncthreads();
.LBB0_722:
	s_and_b32 s18, s2, 2
	s_mulk_i32 s18, 0x4800
	v_add3_u32 v66, s18, v90, v91
	v_add3_u32 v95, s18, v92, v91
	s_setprio 1
	ds_read_b128 v[128:131], v66 offset:0
	ds_read_b128 v[136:139], v95 offset:18432
	ds_read_b128 v[144:147], v66 offset:4608
	ds_read_b128 v[140:143], v95 offset:23040
	s_waitcnt lgkmcnt(2)
	v_mfma_f32_32x32x16_bf16 v[50:65], v[128:131], v[136:139], v[50:65]
	ds_read_b128 v[148:151], v66 offset:32
	s_waitcnt lgkmcnt(2)
	v_mfma_f32_32x32x16_bf16 v[18:33], v[144:147], v[136:139], v[18:33]
	ds_read_b128 v[136:139], v95 offset:18464
	s_waitcnt lgkmcnt(2)
	v_mfma_f32_32x32x16_bf16 v[34:49], v[128:131], v[140:143], v[34:49]
	ds_read_b128 v[128:131], v66 offset:4640
	v_mfma_f32_32x32x16_bf16 v[2:17], v[144:147], v[140:143], v[2:17]
	ds_read_b128 v[140:143], v95 offset:23072
	s_waitcnt lgkmcnt(2)
	v_mfma_f32_32x32x16_bf16 v[50:65], v[148:151], v[136:139], v[50:65]
	ds_read_b128 v[144:147], v66 offset:64
	s_waitcnt lgkmcnt(2)
	v_mfma_f32_32x32x16_bf16 v[18:33], v[128:131], v[136:139], v[18:33]
	ds_read_b128 v[136:139], v95 offset:18496
	s_waitcnt lgkmcnt(2)
	v_mfma_f32_32x32x16_bf16 v[34:49], v[148:151], v[140:143], v[34:49]
	ds_read_b128 v[148:151], v66 offset:4672
	v_mfma_f32_32x32x16_bf16 v[2:17], v[128:131], v[140:143], v[2:17]
	ds_read_b128 v[140:143], v95 offset:23104
	s_waitcnt lgkmcnt(2)
	v_mfma_f32_32x32x16_bf16 v[50:65], v[144:147], v[136:139], v[50:65]
	ds_read_b128 v[128:131], v66 offset:96
	s_waitcnt lgkmcnt(2)
	v_mfma_f32_32x32x16_bf16 v[18:33], v[148:151], v[136:139], v[18:33]
	ds_read_b128 v[136:139], v95 offset:18528
	s_waitcnt lgkmcnt(2)
	v_mfma_f32_32x32x16_bf16 v[34:49], v[144:147], v[140:143], v[34:49]
	ds_read_b128 v[144:147], v66 offset:4704
	v_mfma_f32_32x32x16_bf16 v[2:17], v[148:151], v[140:143], v[2:17]
	ds_read_b128 v[140:143], v95 offset:23136
	s_waitcnt lgkmcnt(2)
	v_mfma_f32_32x32x16_bf16 v[50:65], v[128:131], v[136:139], v[50:65]
	s_waitcnt lgkmcnt(1)
	v_mfma_f32_32x32x16_bf16 v[18:33], v[144:147], v[136:139], v[18:33]
	s_waitcnt lgkmcnt(0)
	v_mfma_f32_32x32x16_bf16 v[34:49], v[128:131], v[140:143], v[34:49]
	v_mfma_f32_32x32x16_bf16 v[2:17], v[144:147], v[140:143], v[2:17]
	s_setprio 0
	s_add_i32 s2, s2, 2
	s_and_b32 s18, s2, 2
	s_add_u32 s16, s16, 0x80
	s_mulk_i32 s18, 0x4800
	s_addc_u32 s17, s17, 0
	v_add_u32_e32 v66, s18, v1
	s_cmpk_lg_i32 s16, 0x700
	s_waitcnt vmcnt(7)
	ds_write_b128 v66, v[96:99]
	v_lshl_add_u64 v[96:97], v[88:89], 0, s[16:17]
	v_add_co_u32_e32 v96, vcc, s24, v96
	s_nop 1
	v_addc_co_u32_e32 v97, vcc, 0, v97, vcc
	global_load_dwordx4 v[96:99], v[96:97], off offset:384
	s_waitcnt vmcnt(7)
	ds_write_b128 v66, v[100:103] offset:4608
	v_lshl_add_u64 v[100:101], v[88:89], 0, s[16:17]
	v_add_co_u32_e32 v100, vcc, s25, v100
	s_nop 1
	v_addc_co_u32_e32 v101, vcc, 0, v101, vcc
	global_load_dwordx4 v[100:103], v[100:101], off offset:384
	s_waitcnt vmcnt(7)
	ds_write_b128 v66, v[104:107] offset:9216
	v_lshl_add_u64 v[104:105], v[88:89], 0, s[16:17]
	v_add_co_u32_e32 v104, vcc, s26, v104
	s_nop 1
	v_addc_co_u32_e32 v105, vcc, 0, v105, vcc
	global_load_dwordx4 v[104:107], v[104:105], off offset:384
	s_waitcnt vmcnt(7)
	ds_write_b128 v66, v[108:111] offset:13824
	v_lshl_add_u64 v[108:109], v[88:89], 0, s[16:17]
	v_add_co_u32_e32 v108, vcc, s27, v108
	s_nop 1
	v_addc_co_u32_e32 v109, vcc, 0, v109, vcc
	global_load_dwordx4 v[108:111], v[108:109], off offset:384
	s_waitcnt vmcnt(7)
	ds_write_b128 v66, v[112:115] offset:18432
	v_lshl_add_u64 v[112:113], v[78:79], 0, s[16:17]
	v_add_co_u32_e32 v112, vcc, s28, v112
	s_nop 1
	v_addc_co_u32_e32 v113, vcc, 0, v113, vcc
	global_load_dwordx4 v[112:115], v[112:113], off offset:128
	s_waitcnt vmcnt(7)
	ds_write_b128 v66, v[116:119] offset:23040
	v_lshl_add_u64 v[116:117], v[78:79], 0, s[16:17]
	v_add_co_u32_e32 v116, vcc, s29, v116
	s_nop 1
	v_addc_co_u32_e32 v117, vcc, 0, v117, vcc
	global_load_dwordx4 v[116:119], v[116:117], off offset:128
	s_waitcnt vmcnt(7)
	ds_write_b128 v66, v[120:123] offset:27648
	v_lshl_add_u64 v[120:121], v[78:79], 0, s[16:17]
	v_add_co_u32_e32 v120, vcc, s30, v120
	s_nop 1
	v_addc_co_u32_e32 v121, vcc, 0, v121, vcc
	global_load_dwordx4 v[120:123], v[120:121], off offset:128
	s_waitcnt vmcnt(7)
	ds_write_b128 v66, v[124:127] offset:32256
	v_lshl_add_u64 v[124:125], v[78:79], 0, s[16:17]
	v_add_co_u32_e32 v124, vcc, s31, v124
	s_nop 1
	v_addc_co_u32_e32 v125, vcc, 0, v125, vcc
	global_load_dwordx4 v[124:127], v[124:125], off offset:128
	s_waitcnt lgkmcnt(0)
	s_barrier
	s_cbranch_scc1 .LBB0_722
;     ...
;   for (int kt = 0; kt < nk; ++kt) {
;     const int kn = (kt + 1 < nk) ? kt + 1 : kt;
;     GM_LOAD2(kn * 64, kn * bkstep)
;     __builtin_amdgcn_sched_barrier(0);
;     const char* As = smem + (kt & 1) * 2 * TILE_B;
;     const char* Bs = As + TILE_B;
;     if constexpr (HOIST) {
;       bf16x8 fa0[4], fa1[4], fb0[4], fb1[4];
; #pragma unroll
;       for (int st = 0; st < 4; ++st) {
;         fa0[st] = *(const bf16x8*)(As + aoff + st * 32);
;         fb0[st] = *(const bf16x8*)(Bs + boff + st * 32);
;         fa1[st] = *(const bf16x8*)(As + aoff + 32 * LSTR + st * 32);
;         fb1[st] = *(const bf16x8*)(Bs + boff + 32 * LSTR + st * 32);
;       }
;       __builtin_amdgcn_sched_barrier(0);
; #pragma unroll
;       for (int st = 0; st < 4; ++st) {
;         acc[0][0] = mfma32(fa0[st], fb0[st], acc[0][0]);
;         acc[0][1] = mfma32(fa0[st], fb1[st], acc[0][1]);
;         acc[1][0] = mfma32(fa1[st], fb0[st], acc[1][0]);
;         acc[1][1] = mfma32(fa1[st], fb1[st], acc[1][1]);
;       }
;     } else {
; #pragma unroll
;       for (int st = 0; st < 4; ++st) {
;         bf16x8 a0 = *(const bf16x8*)(As + aoff + st * 32);
;         bf16x8 a1 = *(const bf16x8*)(As + aoff + 32 * LSTR + st * 32);
;         bf16x8 b0 = *(const bf16x8*)(Bs + boff + st * 32);
;         bf16x8 b1 = *(const bf16x8*)(Bs + boff + 32 * LSTR + st * 32);
;         acc[0][0] = mfma32(a0, b0, acc[0][0]);
;         acc[0][1] = mfma32(a0, b1, acc[0][1]);
;         acc[1][0] = mfma32(a1, b0, acc[1][0]);
;         acc[1][1] = mfma32(a1, b1, acc[1][1]);
;       }
;     }
;     __builtin_amdgcn_sched_barrier(0);
;     {
;       char* Ad = smem + ((kt + 1) & 1) * 2 * TILE_B;
;       GM_STORE(Ad)
;     }
;     __syncthreads();
	s_and_b32 s18, s2, 2
	s_mulk_i32 s18, 0x4800
	v_add3_u32 v66, s18, v90, v91
	v_add3_u32 v95, s18, v92, v91
	s_setprio 1
	ds_read_b128 v[128:131], v66 offset:0
	ds_read_b128 v[136:139], v95 offset:18432
	ds_read_b128 v[144:147], v66 offset:4608
	ds_read_b128 v[140:143], v95 offset:23040
	s_waitcnt lgkmcnt(2)
	v_mfma_f32_32x32x16_bf16 v[50:65], v[128:131], v[136:139], v[50:65]
	ds_read_b128 v[148:151], v66 offset:32
	s_waitcnt lgkmcnt(2)
	v_mfma_f32_32x32x16_bf16 v[18:33], v[144:147], v[136:139], v[18:33]
	ds_read_b128 v[136:139], v95 offset:18464
	s_waitcnt lgkmcnt(2)
	v_mfma_f32_32x32x16_bf16 v[34:49], v[128:131], v[140:143], v[34:49]
	ds_read_b128 v[128:131], v66 offset:4640
	v_mfma_f32_32x32x16_bf16 v[2:17], v[144:147], v[140:143], v[2:17]
	ds_read_b128 v[140:143], v95 offset:23072
	s_waitcnt lgkmcnt(2)
	v_mfma_f32_32x32x16_bf16 v[50:65], v[148:151], v[136:139], v[50:65]
	ds_read_b128 v[144:147], v66 offset:64
	s_waitcnt lgkmcnt(2)
	v_mfma_f32_32x32x16_bf16 v[18:33], v[128:131], v[136:139], v[18:33]
	ds_read_b128 v[136:139], v95 offset:18496
	s_waitcnt lgkmcnt(2)
	v_mfma_f32_32x32x16_bf16 v[34:49], v[148:151], v[140:143], v[34:49]
	ds_read_b128 v[148:151], v66 offset:4672
	v_mfma_f32_32x32x16_bf16 v[2:17], v[128:131], v[140:143], v[2:17]
	ds_read_b128 v[140:143], v95 offset:23104
	s_waitcnt lgkmcnt(2)
	v_mfma_f32_32x32x16_bf16 v[50:65], v[144:147], v[136:139], v[50:65]
	ds_read_b128 v[128:131], v66 offset:96
	s_waitcnt lgkmcnt(2)
	v_mfma_f32_32x32x16_bf16 v[18:33], v[148:151], v[136:139], v[18:33]
	ds_read_b128 v[136:139], v95 offset:18528
	s_waitcnt lgkmcnt(2)
	v_mfma_f32_32x32x16_bf16 v[34:49], v[144:147], v[140:143], v[34:49]
	ds_read_b128 v[144:147], v66 offset:4704
	v_mfma_f32_32x32x16_bf16 v[2:17], v[148:151], v[140:143], v[2:17]
	ds_read_b128 v[140:143], v95 offset:23136
	s_waitcnt lgkmcnt(2)
	v_mfma_f32_32x32x16_bf16 v[50:65], v[128:131], v[136:139], v[50:65]
	s_waitcnt lgkmcnt(1)
	v_mfma_f32_32x32x16_bf16 v[18:33], v[144:147], v[136:139], v[18:33]
	s_waitcnt lgkmcnt(0)
	v_mfma_f32_32x32x16_bf16 v[34:49], v[128:131], v[140:143], v[34:49]
	v_mfma_f32_32x32x16_bf16 v[2:17], v[144:147], v[140:143], v[2:17]
	s_setprio 0
	s_add_i32 s2, s2, 2
	s_and_b32 s18, s2, 2
	s_add_u32 s16, s16, 0x80
	s_mulk_i32 s18, 0x4800
	s_addc_u32 s17, s17, 0
	v_add_u32_e32 v66, s18, v1
	s_waitcnt vmcnt(7)
	ds_write_b128 v66, v[96:99]
	s_waitcnt vmcnt(6)
	ds_write_b128 v66, v[100:103] offset:4608
	s_waitcnt vmcnt(5)
	ds_write_b128 v66, v[104:107] offset:9216
	s_waitcnt vmcnt(4)
	ds_write_b128 v66, v[108:111] offset:13824
	s_waitcnt vmcnt(3)
	ds_write_b128 v66, v[112:115] offset:18432
	s_waitcnt vmcnt(2)
	ds_write_b128 v66, v[116:119] offset:23040
	s_waitcnt vmcnt(1)
	ds_write_b128 v66, v[120:123] offset:27648
	s_waitcnt vmcnt(0)
	ds_write_b128 v66, v[124:127] offset:32256
	s_waitcnt lgkmcnt(0)
	s_barrier
	v_add_co_u32_e32 v104, vcc, 0x10000, v76
	s_nop 0
	s_nop 0
	s_nop 0
	v_addc_co_u32_e32 v105, vcc, 0, v77, vcc
	v_add_co_u32_e32 v108, vcc, 0x20000, v76
	s_nop 0
	v_addc_co_u32_e32 v109, vcc, 0, v77, vcc
	v_add_co_u32_e32 v76, vcc, 0x30000, v76
	s_lshl_b64 s[14:15], s[14:15], 7
	s_nop 0
	v_addc_co_u32_e32 v77, vcc, 0, v77, vcc
	s_nop 0
	v_add_u32_e32 v66, v90, v91
	v_add_u32_e32 v76, v92, v91
	s_setprio 1
	ds_read_b128 v[116:119], v66 offset:36864
	ds_read_b128 v[120:123], v76 offset:55296
	ds_read_b128 v[128:131], v66 offset:41472
	ds_read_b128 v[124:127], v76 offset:59904
	s_waitcnt lgkmcnt(2)
	v_mfma_f32_32x32x16_bf16 v[50:65], v[116:119], v[120:123], v[50:65]
	ds_read_b128 v[136:139], v66 offset:36896
	s_waitcnt lgkmcnt(2)
	v_mfma_f32_32x32x16_bf16 v[18:33], v[128:131], v[120:123], v[18:33]
	ds_read_b128 v[120:123], v76 offset:55328
	s_waitcnt lgkmcnt(2)
	v_mfma_f32_32x32x16_bf16 v[34:49], v[116:119], v[124:127], v[34:49]
	ds_read_b128 v[116:119], v66 offset:41504
	v_mfma_f32_32x32x16_bf16 v[2:17], v[128:131], v[124:127], v[2:17]
	ds_read_b128 v[124:127], v76 offset:59936
	s_waitcnt lgkmcnt(2)
	v_mfma_f32_32x32x16_bf16 v[50:65], v[136:139], v[120:123], v[50:65]
	ds_read_b128 v[128:131], v66 offset:36928
	s_waitcnt lgkmcnt(2)
	v_mfma_f32_32x32x16_bf16 v[18:33], v[116:119], v[120:123], v[18:33]
	ds_read_b128 v[120:123], v76 offset:55360
	s_waitcnt lgkmcnt(2)
	v_mfma_f32_32x32x16_bf16 v[34:49], v[136:139], v[124:127], v[34:49]
	ds_read_b128 v[136:139], v66 offset:41536
	v_mfma_f32_32x32x16_bf16 v[2:17], v[116:119], v[124:127], v[2:17]
	ds_read_b128 v[124:127], v76 offset:59968
	s_waitcnt lgkmcnt(2)
	v_mfma_f32_32x32x16_bf16 v[50:65], v[128:131], v[120:123], v[50:65]
	ds_read_b128 v[116:119], v66 offset:36960
	s_waitcnt lgkmcnt(2)
	v_mfma_f32_32x32x16_bf16 v[18:33], v[136:139], v[120:123], v[18:33]
	ds_read_b128 v[120:123], v76 offset:55392
	s_waitcnt lgkmcnt(2)
	v_mfma_f32_32x32x16_bf16 v[34:49], v[128:131], v[124:127], v[34:49]
	ds_read_b128 v[128:131], v66 offset:41568
	v_mfma_f32_32x32x16_bf16 v[2:17], v[136:139], v[124:127], v[2:17]
	ds_read_b128 v[124:127], v76 offset:60000
	s_waitcnt lgkmcnt(2)
	v_mfma_f32_32x32x16_bf16 v[50:65], v[116:119], v[120:123], v[50:65]
	s_waitcnt lgkmcnt(1)
	v_mfma_f32_32x32x16_bf16 v[18:33], v[128:131], v[120:123], v[18:33]
	s_waitcnt lgkmcnt(0)
	v_mfma_f32_32x32x16_bf16 v[34:49], v[116:119], v[124:127], v[34:49]
	v_mfma_f32_32x32x16_bf16 v[2:17], v[128:131], v[124:127], v[2:17]
	s_setprio 0
	s_waitcnt lgkmcnt(0)
	s_barrier
; __device__ __forceinline__ void acc_to_lds(const f32x16 (&acc)[2][2], float* cs) {
;   const int tid = threadIdx.x, lane = tid & 63, wave = tid >> 6;
;   const int wm = wave >> 1, wn = wave & 1;
; #pragma unroll
;   for (int i = 0; i < 2; ++i)
; #pragma unroll
;     for (int j = 0; j < 2; ++j)
; #pragma unroll
;       for (int r = 0; r < 16; ++r) {
;         int row = wm * 64 + i * 32 + (r & 3) + 8 * (r >> 2) + 4 * (lane >> 5);
;         int col = wn * 64 + j * 32 + (lane & 31);
;         cs[row * CSTR + col] = acc[i][j][r];
;       }
;   __syncthreads();
; template <bool WIDE>
; __device__ __forceinline__ void outproj_tile(const Params& P, int l, int mt, int nt, char* smem) {
;     ...
;     int tid_ = threadIdx.x;
;     asm volatile("" : "+v"(tid_));
;     const int lane = tid_ & 63, wave = tid_ >> 6;
;     const int r = 32 * wave + (lane & 31), half = lane >> 5;
;     const size_t grow = (size_t)mt * 128 + r;
;     const bool isctx = grow >= NLAT;
;     const int modrow = isctx ? 8 : (int)(grow >> 12);
;     const int col = (nt + hsel) * 128 + half * 64;
;     const float* g1 = WSP(float, OFF_MOD) + ((size_t)l * 9 + modrow) * 6144 + 2048 + col;
;     const float* xin;
;     float* xo;
;     if (!isctx) { xin = (l == 0 ? P.x : P.out) + grow * DM + col; xo = P.out + grow * DM + col; }
;     else { xin = (l == 0 ? P.ctx : WSP(float, OFF_XC)) + (grow - NLAT) * DM + col; xo = WSP(float, OFF_XC) + (grow - NLAT) * DM + col; }
	ds_write2_b32 v93, v50, v34 offset1:32
	ds_write2_b32 v93, v51, v35 offset0:132 offset1:164
	v_add_u32_e32 v34, 0x400, v93
	ds_write2_b32 v34, v52, v36 offset0:8 offset1:40
	ds_write2_b32 v34, v53, v37 offset0:140 offset1:172
	v_add_u32_e32 v34, 0x1000, v93
	ds_write2_b32 v34, v54, v38 offset0:32 offset1:64
	ds_write2_b32 v34, v55, v39 offset0:164 offset1:196
	v_add_u32_e32 v34, 0x1400, v93
	ds_write2_b32 v34, v56, v40 offset0:40 offset1:72
	ds_write2_b32 v34, v57, v41 offset0:172 offset1:204
	v_add_u32_e32 v34, 0x2000, v93
	ds_write2_b32 v34, v58, v42 offset0:64 offset1:96
	ds_write2_b32 v34, v59, v43 offset0:196 offset1:228
	v_add_u32_e32 v34, 0x2400, v93
	ds_write2_b32 v34, v60, v44 offset0:72 offset1:104
	ds_write2_b32 v34, v61, v45 offset0:204 offset1:236
	v_add_u32_e32 v34, 0x3000, v93
	ds_write2_b32 v34, v62, v46 offset0:96 offset1:128
	v_add_u32_e32 v34, 0x3200, v93
	ds_write2_b32 v34, v63, v47 offset0:100 offset1:132
	v_add_u32_e32 v34, 0x3400, v93
	ds_write2_b32 v34, v64, v48 offset0:104 offset1:136
	v_add_u32_e32 v34, 0x3600, v93
	ds_write2_b32 v34, v65, v49 offset0:108 offset1:140
	v_add_u32_e32 v34, 0x4000, v93
	ds_write2_b32 v34, v18, v2 offset0:128 offset1:160
	v_add_u32_e32 v2, 0x4400, v93
	ds_write2_b32 v2, v19, v3 offset0:4 offset1:36
	ds_write2_b32 v2, v20, v4 offset0:136 offset1:168
	v_add_u32_e32 v2, 0x4800, v93
	ds_write2_b32 v2, v21, v5 offset0:12 offset1:44
	v_add_u32_e32 v2, 0x5000, v93
	ds_write2_b32 v2, v22, v6 offset0:160 offset1:192
	v_add_u32_e32 v2, 0x5400, v93
	ds_write2_b32 v2, v23, v7 offset0:36 offset1:68
	ds_write2_b32 v2, v24, v8 offset0:168 offset1:200
	v_add_u32_e32 v2, 0x5800, v93
	ds_write2_b32 v2, v25, v9 offset0:44 offset1:76
	v_add_u32_e32 v2, 0x6000, v93
	ds_write2_b32 v2, v26, v10 offset0:192 offset1:224
	v_add_u32_e32 v2, 0x6400, v93
	ds_write2_b32 v2, v27, v11 offset0:68 offset1:100
	ds_write2_b32 v2, v28, v12 offset0:200 offset1:232
	v_add_u32_e32 v2, 0x6800, v93
	ds_write2_b32 v2, v29, v13 offset0:76 offset1:108
	v_add_u32_e32 v2, 0x7200, v93
	ds_write2_b32 v2, v30, v14 offset0:96 offset1:128
	v_add_u32_e32 v2, 0x7400, v93
	ds_write2_b32 v2, v31, v15 offset0:100 offset1:132
	v_add_u32_e32 v2, 0x7600, v93
	ds_write2_b32 v2, v32, v16 offset0:104 offset1:136
	v_add_u32_e32 v2, 0x7800, v93
	v_mov_b32_e32 v12, v134
	ds_write2_b32 v2, v33, v17 offset0:108 offset1:140
	s_waitcnt lgkmcnt(0)
	s_barrier
	s_nop 0
	v_ashrrev_i32_e32 v2, 1, v12
	v_bfi_b32 v2, s33, v2, v12
	v_ashrrev_i32_e32 v3, 31, v2
	v_lshl_add_u64 v[4:5], s[14:15], 0, v[2:3]
	v_cmp_gt_u64_e32 vcc, s[10:11], v[4:5]
	v_lshlrev_b64 v[10:11], 10, v[4:5]
	s_and_saveexec_b64 s[14:15], vcc
	s_xor_b64 s[14:15], exec, s[14:15]
	s_cbranch_execz .LBB0_725
	v_readlane_b32 s56, v253, 21
	v_lshlrev_b64 v[8:9], 2, v[10:11]
	v_readlane_b32 s57, v253, 22
	v_readlane_b32 s58, v253, 23
	v_readlane_b32 s59, v253, 24
	v_lshl_add_u64 v[6:7], s[56:57], 0, v[8:9]
	v_lshl_add_u64 v[8:9], s[88:89], 0, v[8:9]
	v_readlane_b32 s60, v253, 25
	v_readlane_b32 s61, v253, 26
	v_readlane_b32 s62, v253, 27
	v_readlane_b32 s63, v253, 28
	v_readlane_b32 s64, v253, 29
	v_readlane_b32 s65, v253, 30
	v_readlane_b32 s66, v253, 31
	v_readlane_b32 s67, v253, 32
	v_readlane_b32 s68, v253, 33
	v_readlane_b32 s69, v253, 34
	v_readlane_b32 s70, v253, 35
	v_readlane_b32 s71, v253, 36

;     ...
;   for (int kt = 0; kt < nk; ++kt) {
;     const int kn = (kt + 1 < nk) ? kt + 1 : kt;
;     GM_LOAD2(kn * 64, kn * bkstep)
;     __builtin_amdgcn_sched_barrier(0);
;     const char* As = smem + (kt & 1) * 2 * TILE_B;
;     const char* Bs = As + TILE_B;
;     if constexpr (HOIST) {
;       bf16x8 fa0[4], fa1[4], fb0[4], fb1[4];
; #pragma unroll
;       for (int st = 0; st < 4; ++st) {
;         fa0[st] = *(const bf16x8*)(As + aoff + st * 32);
;         fb0[st] = *(const bf16x8*)(Bs + boff + st * 32);
;         fa1[st] = *(const bf16x8*)(As + aoff + 32 * LSTR + st * 32);
;         fb1[st] = *(const bf16x8*)(Bs + boff + 32 * LSTR + st * 32);
;       }
;       __builtin_amdgcn_sched_barrier(0);
; #pragma unroll
;       for (int st = 0; st < 4; ++st) {
;         acc[0][0] = mfma32(fa0[st], fb0[st], acc[0][0]);
;         acc[0][1] = mfma32(fa0[st], fb1[st], acc[0][1]);
;         acc[1][0] = mfma32(fa1[st], fb0[st], acc[1][0]);
;         acc[1][1] = mfma32(fa1[st], fb1[st], acc[1][1]);
;       }
;     } else {
; #pragma unroll
;       for (int st = 0; st < 4; ++st) {
;         bf16x8 a0 = *(const bf16x8*)(As + aoff + st * 32);
;         bf16x8 a1 = *(const bf16x8*)(As + aoff + 32 * LSTR + st * 32);
;         bf16x8 b0 = *(const bf16x8*)(Bs + boff + st * 32);
;         bf16x8 b1 = *(const bf16x8*)(Bs + boff + 32 * LSTR + st * 32);
;         acc[0][0] = mfma32(a0, b0, acc[0][0]);
;         acc[0][1] = mfma32(a0, b1, acc[0][1]);
;         acc[1][0] = mfma32(a1, b0, acc[1][0]);
;         acc[1][1] = mfma32(a1, b1, acc[1][1]);
;       }
;     }
;     __builtin_amdgcn_sched_barrier(0);
;     {
;       char* Ad = smem + ((kt + 1) & 1) * 2 * TILE_B;
;       GM_STORE(Ad)
;     }
;     __syncthreads();
.LBB0_1121:
	s_and_b32 s14, s15, 2
	s_mulk_i32 s14, 0x4800
	v_add3_u32 v66, s14, v94, v95
	v_add3_u32 v135, s14, v96, v95
	s_setprio 1
	ds_read_b128 v[130:133], v66 offset:0
	ds_read_b128 v[136:139], v135 offset:18432
	ds_read_b128 v[144:147], v66 offset:4608
	ds_read_b128 v[140:143], v135 offset:23040
	s_waitcnt lgkmcnt(2)
	v_mfma_f32_32x32x16_bf16 v[50:65], v[130:133], v[136:139], v[50:65]
	ds_read_b128 v[148:151], v66 offset:32
	s_waitcnt lgkmcnt(2)
	v_mfma_f32_32x32x16_bf16 v[2:17], v[144:147], v[136:139], v[2:17]
	ds_read_b128 v[136:139], v135 offset:18464
	s_waitcnt lgkmcnt(2)
	v_mfma_f32_32x32x16_bf16 v[18:33], v[130:133], v[140:143], v[18:33]
	ds_read_b128 v[130:133], v66 offset:4640
	v_mfma_f32_32x32x16_bf16 v[34:49], v[144:147], v[140:143], v[34:49]
	ds_read_b128 v[140:143], v135 offset:23072
	s_waitcnt lgkmcnt(2)
	v_mfma_f32_32x32x16_bf16 v[50:65], v[148:151], v[136:139], v[50:65]
	ds_read_b128 v[144:147], v66 offset:64
	s_waitcnt lgkmcnt(2)
	v_mfma_f32_32x32x16_bf16 v[2:17], v[130:133], v[136:139], v[2:17]
	ds_read_b128 v[136:139], v135 offset:18496
	s_waitcnt lgkmcnt(2)
	v_mfma_f32_32x32x16_bf16 v[18:33], v[148:151], v[140:143], v[18:33]
	ds_read_b128 v[148:151], v66 offset:4672
	v_mfma_f32_32x32x16_bf16 v[34:49], v[130:133], v[140:143], v[34:49]
	ds_read_b128 v[140:143], v135 offset:23104
	s_waitcnt lgkmcnt(2)
	v_mfma_f32_32x32x16_bf16 v[50:65], v[144:147], v[136:139], v[50:65]
	ds_read_b128 v[130:133], v66 offset:96
	s_waitcnt lgkmcnt(2)
	v_mfma_f32_32x32x16_bf16 v[2:17], v[148:151], v[136:139], v[2:17]
	ds_read_b128 v[136:139], v135 offset:18528
	s_waitcnt lgkmcnt(2)
	v_mfma_f32_32x32x16_bf16 v[18:33], v[144:147], v[140:143], v[18:33]
	ds_read_b128 v[144:147], v66 offset:4704
	v_mfma_f32_32x32x16_bf16 v[34:49], v[148:151], v[140:143], v[34:49]
	ds_read_b128 v[140:143], v135 offset:23136
	s_waitcnt lgkmcnt(2)
	v_mfma_f32_32x32x16_bf16 v[50:65], v[130:133], v[136:139], v[50:65]
	s_waitcnt lgkmcnt(1)
	v_mfma_f32_32x32x16_bf16 v[2:17], v[144:147], v[136:139], v[2:17]
	s_waitcnt lgkmcnt(0)
	v_mfma_f32_32x32x16_bf16 v[18:33], v[130:133], v[140:143], v[18:33]
	v_mfma_f32_32x32x16_bf16 v[34:49], v[144:147], v[140:143], v[34:49]
	s_setprio 0
	s_add_i32 s15, s15, 2
	s_and_b32 s14, s15, 2
	s_mulk_i32 s14, 0x4800
	v_add_u32_e32 v66, s14, v1
	v_lshl_add_u64 v[90:91], v[90:91], 0, s[4:5]
	v_lshl_add_u64 v[92:93], v[92:93], 0, s[10:11]
	s_cmp_lg_u32 s15, 60
	s_waitcnt vmcnt(7)
	ds_write_b128 v66, v[98:101]
	v_lshl_add_u64 v[98:99], v[92:93], 0, v[68:69]
	v_add_co_u32_e32 v98, vcc, s26, v98
	s_nop 1
	v_addc_co_u32_e32 v99, vcc, 0, v99, vcc
	global_load_dwordx4 v[98:101], v[98:99], off offset:384
	s_waitcnt vmcnt(7)
	ds_write_b128 v66, v[102:105] offset:4608
	v_lshl_add_u64 v[102:103], v[92:93], 0, v[68:69]
	v_add_co_u32_e32 v102, vcc, s27, v102
	s_nop 1
	v_addc_co_u32_e32 v103, vcc, 0, v103, vcc
	global_load_dwordx4 v[102:105], v[102:103], off offset:384
	s_waitcnt vmcnt(7)
	ds_write_b128 v66, v[106:109] offset:9216
	v_lshl_add_u64 v[106:107], v[92:93], 0, v[68:69]
	v_add_co_u32_e32 v106, vcc, s28, v106
	s_nop 1
	v_addc_co_u32_e32 v107, vcc, 0, v107, vcc
	global_load_dwordx4 v[106:109], v[106:107], off offset:384
	s_waitcnt vmcnt(7)
	ds_write_b128 v66, v[110:113] offset:13824
	v_lshl_add_u64 v[110:111], v[92:93], 0, v[68:69]
	v_add_co_u32_e32 v110, vcc, s29, v110
	s_nop 1
	v_addc_co_u32_e32 v111, vcc, 0, v111, vcc
	global_load_dwordx4 v[110:113], v[110:111], off offset:384
	s_waitcnt vmcnt(7)
	ds_write_b128 v66, v[114:117] offset:18432
	v_lshl_add_u64 v[114:115], v[90:91], 0, v[68:69]
	v_add_co_u32_e32 v114, vcc, s30, v114
	s_nop 1
	v_addc_co_u32_e32 v115, vcc, 0, v115, vcc
	global_load_dwordx4 v[114:117], v[114:115], off offset:-4096
	s_waitcnt vmcnt(7)
	ds_write_b128 v66, v[118:121] offset:23040
	v_lshl_add_u64 v[118:119], v[90:91], 0, v[68:69]
	v_add_co_u32_e32 v118, vcc, s30, v118
	s_nop 1
	v_addc_co_u32_e32 v119, vcc, 0, v119, vcc
	global_load_dwordx4 v[118:121], v[118:119], off
	s_waitcnt vmcnt(7)
	ds_write_b128 v66, v[122:125] offset:27648
	v_lshl_add_u64 v[122:123], v[90:91], 0, v[68:69]
	v_add_co_u32_e32 v122, vcc, s31, v122
	s_nop 1
	v_addc_co_u32_e32 v123, vcc, 0, v123, vcc
	global_load_dwordx4 v[122:125], v[122:123], off offset:-4096
	s_waitcnt vmcnt(7)
	ds_write_b128 v66, v[126:129] offset:32256
	v_lshl_add_u64 v[126:127], v[90:91], 0, v[68:69]
	v_add_co_u32_e32 v126, vcc, s31, v126
	s_nop 1
	v_addc_co_u32_e32 v127, vcc, 0, v127, vcc
	global_load_dwordx4 v[126:129], v[126:127], off
	s_waitcnt lgkmcnt(0)
	s_barrier
	s_cbranch_scc1 .LBB0_1121
;     ...
;   for (int kt = 0; kt < nk; ++kt) {
;     const int kn = (kt + 1 < nk) ? kt + 1 : kt;
;     GM_LOAD2(kn * 64, kn * bkstep)
;     __builtin_amdgcn_sched_barrier(0);
;     const char* As = smem + (kt & 1) * 2 * TILE_B;
;     const char* Bs = As + TILE_B;
;     if constexpr (HOIST) {
;       bf16x8 fa0[4], fa1[4], fb0[4], fb1[4];
; #pragma unroll
;       for (int st = 0; st < 4; ++st) {
;         fa0[st] = *(const bf16x8*)(As + aoff + st * 32);
;         fb0[st] = *(const bf16x8*)(Bs + boff + st * 32);
;         fa1[st] = *(const bf16x8*)(As + aoff + 32 * LSTR + st * 32);
;         fb1[st] = *(const bf16x8*)(Bs + boff + 32 * LSTR + st * 32);
;       }
;       __builtin_amdgcn_sched_barrier(0);
; #pragma unroll
;       for (int st = 0; st < 4; ++st) {
;         acc[0][0] = mfma32(fa0[st], fb0[st], acc[0][0]);
;         acc[0][1] = mfma32(fa0[st], fb1[st], acc[0][1]);
;         acc[1][0] = mfma32(fa1[st], fb0[st], acc[1][0]);
;         acc[1][1] = mfma32(fa1[st], fb1[st], acc[1][1]);
;       }
;     } else {
; #pragma unroll
;       for (int st = 0; st < 4; ++st) {
;         bf16x8 a0 = *(const bf16x8*)(As + aoff + st * 32);
;         bf16x8 a1 = *(const bf16x8*)(As + aoff + 32 * LSTR + st * 32);
;         bf16x8 b0 = *(const bf16x8*)(Bs + boff + st * 32);
;         bf16x8 b1 = *(const bf16x8*)(Bs + boff + 32 * LSTR + st * 32);
;         acc[0][0] = mfma32(a0, b0, acc[0][0]);
;         acc[0][1] = mfma32(a0, b1, acc[0][1]);
;         acc[1][0] = mfma32(a1, b0, acc[1][0]);
;         acc[1][1] = mfma32(a1, b1, acc[1][1]);
;       }
;     }
;     __builtin_amdgcn_sched_barrier(0);
;     {
;       char* Ad = smem + ((kt + 1) & 1) * 2 * TILE_B;
;       GM_STORE(Ad)
;     }
;     __syncthreads();
	s_and_b32 s14, s15, 2
	s_mulk_i32 s14, 0x4800
	v_add3_u32 v66, s14, v94, v95
	v_add3_u32 v135, s14, v96, v95
	s_setprio 1
	ds_read_b128 v[130:133], v66 offset:0
	ds_read_b128 v[136:139], v135 offset:18432
	ds_read_b128 v[144:147], v66 offset:4608
	ds_read_b128 v[140:143], v135 offset:23040
	s_waitcnt lgkmcnt(2)
	v_mfma_f32_32x32x16_bf16 v[50:65], v[130:133], v[136:139], v[50:65]
	ds_read_b128 v[148:151], v66 offset:32
	s_waitcnt lgkmcnt(2)
	v_mfma_f32_32x32x16_bf16 v[2:17], v[144:147], v[136:139], v[2:17]
	ds_read_b128 v[136:139], v135 offset:18464
	s_waitcnt lgkmcnt(2)
	v_mfma_f32_32x32x16_bf16 v[18:33], v[130:133], v[140:143], v[18:33]
	ds_read_b128 v[130:133], v66 offset:4640
	v_mfma_f32_32x32x16_bf16 v[34:49], v[144:147], v[140:143], v[34:49]
	ds_read_b128 v[140:143], v135 offset:23072
	s_waitcnt lgkmcnt(2)
	v_mfma_f32_32x32x16_bf16 v[50:65], v[148:151], v[136:139], v[50:65]
	ds_read_b128 v[144:147], v66 offset:64
	s_waitcnt lgkmcnt(2)
	v_mfma_f32_32x32x16_bf16 v[2:17], v[130:133], v[136:139], v[2:17]
	ds_read_b128 v[136:139], v135 offset:18496
	s_waitcnt lgkmcnt(2)
	v_mfma_f32_32x32x16_bf16 v[18:33], v[148:151], v[140:143], v[18:33]
	ds_read_b128 v[148:151], v66 offset:4672
	v_mfma_f32_32x32x16_bf16 v[34:49], v[130:133], v[140:143], v[34:49]
	ds_read_b128 v[140:143], v135 offset:23104
	s_waitcnt lgkmcnt(2)
	v_mfma_f32_32x32x16_bf16 v[50:65], v[144:147], v[136:139], v[50:65]
	ds_read_b128 v[130:133], v66 offset:96
	s_waitcnt lgkmcnt(2)
	v_mfma_f32_32x32x16_bf16 v[2:17], v[148:151], v[136:139], v[2:17]
	ds_read_b128 v[136:139], v135 offset:18528
	s_waitcnt lgkmcnt(2)
	v_mfma_f32_32x32x16_bf16 v[18:33], v[144:147], v[140:143], v[18:33]
	ds_read_b128 v[144:147], v66 offset:4704
	v_mfma_f32_32x32x16_bf16 v[34:49], v[148:151], v[140:143], v[34:49]
	ds_read_b128 v[140:143], v135 offset:23136
	s_waitcnt lgkmcnt(2)
	v_mfma_f32_32x32x16_bf16 v[50:65], v[130:133], v[136:139], v[50:65]
	s_waitcnt lgkmcnt(1)
	v_mfma_f32_32x32x16_bf16 v[2:17], v[144:147], v[136:139], v[2:17]
	s_waitcnt lgkmcnt(0)
	v_mfma_f32_32x32x16_bf16 v[18:33], v[130:133], v[140:143], v[18:33]
	v_mfma_f32_32x32x16_bf16 v[34:49], v[144:147], v[140:143], v[34:49]
	s_setprio 0
	s_add_i32 s15, s15, 2
	s_and_b32 s14, s15, 2
	s_mulk_i32 s14, 0x4800
	v_add_u32_e32 v66, s14, v1
	v_lshl_add_u64 v[90:91], v[90:91], 0, s[4:5]
	v_lshl_add_u64 v[92:93], v[92:93], 0, s[10:11]
	s_waitcnt vmcnt(7)
	ds_write_b128 v66, v[98:101]
	s_waitcnt vmcnt(6)
	ds_write_b128 v66, v[102:105] offset:4608
	s_waitcnt vmcnt(5)
	ds_write_b128 v66, v[106:109] offset:9216
	s_waitcnt vmcnt(4)
	ds_write_b128 v66, v[110:113] offset:13824
	s_waitcnt vmcnt(3)
	ds_write_b128 v66, v[114:117] offset:18432
	s_waitcnt vmcnt(2)
	ds_write_b128 v66, v[118:121] offset:23040
	s_waitcnt vmcnt(1)
	ds_write_b128 v66, v[122:125] offset:27648
	s_waitcnt vmcnt(0)
	ds_write_b128 v66, v[126:129] offset:32256
	s_waitcnt lgkmcnt(0)
	s_barrier
	v_add_co_u32_e32 v102, vcc, 0x3e0000, v80
	s_nop 0
	s_nop 0
	s_nop 0
	v_addc_co_u32_e32 v103, vcc, 0, v81, vcc
	v_add_co_u32_e32 v106, vcc, 0x3e1000, v80
	s_nop 1
	v_addc_co_u32_e32 v107, vcc, 0, v81, vcc
	v_add_co_u32_e32 v110, vcc, 0x3e2000, v80
	s_nop 0
	v_addc_co_u32_e32 v111, vcc, 0, v81, vcc
	v_add_co_u32_e32 v80, vcc, 0x3e3000, v80
	s_nop 1
	v_addc_co_u32_e32 v81, vcc, 0, v81, vcc
	s_nop 0
	v_add_u32_e32 v66, v94, v95
	v_add_u32_e32 v80, v96, v95
	s_setprio 1
	ds_read_b128 v[118:121], v66 offset:36864
	ds_read_b128 v[122:125], v80 offset:55296
	ds_read_b128 v[130:133], v66 offset:41472
	ds_read_b128 v[126:129], v80 offset:59904
	s_waitcnt lgkmcnt(2)
	v_mfma_f32_32x32x16_bf16 v[50:65], v[118:121], v[122:125], v[50:65]
	ds_read_b128 v[136:139], v66 offset:36896
	s_waitcnt lgkmcnt(2)
	v_mfma_f32_32x32x16_bf16 v[2:17], v[130:133], v[122:125], v[2:17]
	ds_read_b128 v[122:125], v80 offset:55328
	s_waitcnt lgkmcnt(2)
	v_mfma_f32_32x32x16_bf16 v[18:33], v[118:121], v[126:129], v[18:33]
	ds_read_b128 v[118:121], v66 offset:41504
	v_mfma_f32_32x32x16_bf16 v[34:49], v[130:133], v[126:129], v[34:49]
	ds_read_b128 v[126:129], v80 offset:59936
	s_waitcnt lgkmcnt(2)
	v_mfma_f32_32x32x16_bf16 v[50:65], v[136:139], v[122:125], v[50:65]
	ds_read_b128 v[130:133], v66 offset:36928
	s_waitcnt lgkmcnt(2)
	v_mfma_f32_32x32x16_bf16 v[2:17], v[118:121], v[122:125], v[2:17]
	ds_read_b128 v[122:125], v80 offset:55360
	s_waitcnt lgkmcnt(2)
	v_mfma_f32_32x32x16_bf16 v[18:33], v[136:139], v[126:129], v[18:33]
	ds_read_b128 v[136:139], v66 offset:41536
	v_mfma_f32_32x32x16_bf16 v[34:49], v[118:121], v[126:129], v[34:49]
	ds_read_b128 v[126:129], v80 offset:59968
	s_waitcnt lgkmcnt(2)
	v_mfma_f32_32x32x16_bf16 v[50:65], v[130:133], v[122:125], v[50:65]
	ds_read_b128 v[118:121], v66 offset:36960
	s_waitcnt lgkmcnt(2)
	v_mfma_f32_32x32x16_bf16 v[2:17], v[136:139], v[122:125], v[2:17]
	ds_read_b128 v[122:125], v80 offset:55392
	s_waitcnt lgkmcnt(2)
	v_mfma_f32_32x32x16_bf16 v[18:33], v[130:133], v[126:129], v[18:33]
	ds_read_b128 v[130:133], v66 offset:41568
	v_mfma_f32_32x32x16_bf16 v[34:49], v[136:139], v[126:129], v[34:49]
	ds_read_b128 v[126:129], v80 offset:60000
	s_waitcnt lgkmcnt(2)
	v_mfma_f32_32x32x16_bf16 v[50:65], v[118:121], v[122:125], v[50:65]
	s_waitcnt lgkmcnt(1)
	v_mfma_f32_32x32x16_bf16 v[2:17], v[130:133], v[122:125], v[2:17]
	s_waitcnt lgkmcnt(0)
	v_mfma_f32_32x32x16_bf16 v[18:33], v[118:121], v[126:129], v[18:33]
	v_mfma_f32_32x32x16_bf16 v[34:49], v[130:133], v[126:129], v[34:49]
	s_setprio 0
	s_waitcnt lgkmcnt(0)
	s_barrier
; __device__ __forceinline__ void acc_to_lds(const f32x16 (&acc)[2][2], float* cs) {
;   const int tid = threadIdx.x, lane = tid & 63, wave = tid >> 6;
;   const int wm = wave >> 1, wn = wave & 1;
; #pragma unroll
;   for (int i = 0; i < 2; ++i)
; #pragma unroll
;     for (int j = 0; j < 2; ++j)
; #pragma unroll
;       for (int r = 0; r < 16; ++r) {
;         int row = wm * 64 + i * 32 + (r & 3) + 8 * (r >> 2) + 4 * (lane >> 5);
;         int col = wn * 64 + j * 32 + (lane & 31);
;         cs[row * CSTR + col] = acc[i][j][r];
;       }
;   __syncthreads();
; __device__ __forceinline__ void epi_plain(const float* cs, u16* out, size_t ld, size_t row0, int col0) {
;   int tid_ = threadIdx.x;
;   asm volatile("" : "+v"(tid_));
;   const int lane = tid_ & 63, wave = tid_ >> 6;
;   const int r = 32 * wave + (lane & 31), half = lane >> 5;
;   const float* src = cs + r * CSTR + half * 64;
;   u16* dst = out + (row0 + r) * ld + col0 + half * 64;
; #pragma unroll
;   for (int q = 0; q < 8; ++q) {
;     float4 a = *(const float4*)(src + q * 8);
;     float4 b = *(const float4*)(src + q * 8 + 4);
;     uint4 o;
;     o.x = pack2(a.x, a.y); o.y = pack2(a.z, a.w); o.z = pack2(b.x, b.y); o.w = pack2(b.z, b.w);
;     *(uint4*)(dst + q * 8) = o;
;   }
; }
; __device__ __forceinline__ void run_phase(const Params& P, int ph, char* smem) {
;     ...
;         for (int it = blockIdx.x; it < 16 * 2 * 8; it += gridDim.x) expert2_tile_narrow(P, it >> 4, 32 + ((it >> 3) & 1), it & 7, smem);
	ds_write2_b32 v97, v50, v18 offset1:32
	ds_write2_b32 v97, v51, v19 offset0:132 offset1:164
	v_add_u32_e32 v18, 0x400, v97
	ds_write2_b32 v18, v52, v20 offset0:8 offset1:40
	ds_write2_b32 v18, v53, v21 offset0:140 offset1:172
	v_add_u32_e32 v18, 0x1000, v97
	ds_write2_b32 v18, v54, v22 offset0:32 offset1:64
	ds_write2_b32 v18, v55, v23 offset0:164 offset1:196
	v_add_u32_e32 v18, 0x1400, v97
	ds_write2_b32 v18, v56, v24 offset0:40 offset1:72
	ds_write2_b32 v18, v57, v25 offset0:172 offset1:204
	v_add_u32_e32 v18, 0x2000, v97
	ds_write2_b32 v18, v58, v26 offset0:64 offset1:96
	ds_write2_b32 v18, v59, v27 offset0:196 offset1:228
	v_add_u32_e32 v18, 0x2400, v97
	ds_write2_b32 v18, v60, v28 offset0:72 offset1:104
	ds_write2_b32 v18, v61, v29 offset0:204 offset1:236
	v_add_u32_e32 v18, 0x3000, v97
	ds_write2_b32 v18, v62, v30 offset0:96 offset1:128
	v_add_u32_e32 v18, 0x3200, v97
	ds_write2_b32 v18, v63, v31 offset0:100 offset1:132
	v_add_u32_e32 v18, 0x3400, v97
	ds_write2_b32 v18, v64, v32 offset0:104 offset1:136
	v_add_u32_e32 v18, 0x3600, v97
	ds_write2_b32 v18, v65, v33 offset0:108 offset1:140
	v_add_u32_e32 v18, 0x4000, v97
	ds_write2_b32 v18, v2, v34 offset0:128 offset1:160
	v_add_u32_e32 v2, 0x4400, v97
	ds_write2_b32 v2, v3, v35 offset0:4 offset1:36
	ds_write2_b32 v2, v4, v36 offset0:136 offset1:168
	v_add_u32_e32 v2, 0x4800, v97
	ds_write2_b32 v2, v5, v37 offset0:12 offset1:44
	v_add_u32_e32 v2, 0x5000, v97
	ds_write2_b32 v2, v6, v38 offset0:160 offset1:192
	v_add_u32_e32 v2, 0x5400, v97
	ds_write2_b32 v2, v7, v39 offset0:36 offset1:68
	ds_write2_b32 v2, v8, v40 offset0:168 offset1:200
	v_add_u32_e32 v2, 0x5800, v97
	ds_write2_b32 v2, v9, v41 offset0:44 offset1:76
	v_add_u32_e32 v2, 0x6000, v97
	ds_write2_b32 v2, v10, v42 offset0:192 offset1:224
	v_add_u32_e32 v2, 0x6400, v97
	ds_write2_b32 v2, v11, v43 offset0:68 offset1:100
	ds_write2_b32 v2, v12, v44 offset0:200 offset1:232
	v_add_u32_e32 v2, 0x6800, v97
	ds_write2_b32 v2, v13, v45 offset0:76 offset1:108
	v_add_u32_e32 v2, 0x7200, v97
	ds_write2_b32 v2, v14, v46 offset0:96 offset1:128
	v_add_u32_e32 v2, 0x7400, v97
	ds_write2_b32 v2, v15, v47 offset0:100 offset1:132
	v_add_u32_e32 v2, 0x7600, v97
	ds_write2_b32 v2, v16, v48 offset0:104 offset1:136
	v_add_u32_e32 v2, 0x7800, v97
	v_mov_b32_e32 v3, v134
	ds_write2_b32 v2, v17, v49 offset0:108 offset1:140
	s_waitcnt lgkmcnt(0)
	s_barrier
	s_lshl_b32 s2, s2, 8
	v_ashrrev_i32_e32 v2, 1, v3
	v_bfi_b32 v2, s33, v2, v3
	v_lshlrev_b32_e32 v3, 1, v3
	v_and_b32_e32 v5, 64, v3
	v_ashrrev_i32_e32 v3, 31, v2
	v_mul_lo_u32 v4, v2, s16
	v_lshl_add_u64 v[2:3], s[12:13], 0, v[2:3]
	v_lshlrev_b64 v[2:3], 11, v[2:3]
	v_lshl_add_u64 v[2:3], s[0:1], 0, v[2:3]
	v_lshl_add_u32 v20, v5, 2, v4
	v_lshl_add_u64 v[6:7], v[2:3], 0, s[2:3]
	v_lshlrev_b32_e32 v66, 1, v5
	ds_read_b128 v[2:5], v20
	v_lshl_add_u64 v[18:19], v[6:7], 0, v[66:67]
	ds_read_b128 v[6:9], v20 offset:16
	ds_read_b128 v[10:13], v20 offset:32
	ds_read_b128 v[14:17], v20 offset:48
	s_waitcnt lgkmcnt(3)
	v_cvt_pk_bf16_f32 v2, v2, v3
	v_cvt_pk_bf16_f32 v3, v4, v5
	s_waitcnt lgkmcnt(2)
	v_cvt_pk_bf16_f32 v4, v6, v7
	v_cvt_pk_bf16_f32 v5, v8, v9
	global_store_dwordx4 v[18:19], v[2:5], off
	ds_read_b128 v[6:9], v20 offset:64
	s_add_i32 s35, s35, s94
	s_waitcnt lgkmcnt(2)
	v_cvt_pk_bf16_f32 v2, v10, v11
	v_cvt_pk_bf16_f32 v3, v12, v13
	s_waitcnt lgkmcnt(1)
	v_cvt_pk_bf16_f32 v4, v14, v15
	v_cvt_pk_bf16_f32 v5, v16, v17
	ds_read_b128 v[10:13], v20 offset:80
	global_store_dwordx4 v[18:19], v[2:5], off offset:16
	s_add_i32 s34, s34, s94
	s_add_i32 s19, s19, s20
	s_waitcnt lgkmcnt(1)
	v_cvt_pk_bf16_f32 v2, v6, v7
	v_cvt_pk_bf16_f32 v3, v8, v9
	s_waitcnt lgkmcnt(0)
	v_cvt_pk_bf16_f32 v4, v10, v11
	v_cvt_pk_bf16_f32 v5, v12, v13
	ds_read_b128 v[6:9], v20 offset:96
	ds_read_b128 v[10:13], v20 offset:112
	global_store_dwordx4 v[18:19], v[2:5], off offset:32
	s_cmpk_lt_i32 s35, 0x100
	ds_read_b128 v[14:17], v20 offset:240
	s_waitcnt lgkmcnt(2)
	v_cvt_pk_bf16_f32 v2, v6, v7
	v_cvt_pk_bf16_f32 v3, v8, v9
	s_waitcnt lgkmcnt(1)
	v_cvt_pk_bf16_f32 v4, v10, v11
	v_cvt_pk_bf16_f32 v5, v12, v13
	ds_read_b128 v[6:9], v20 offset:128
	ds_read_b128 v[10:13], v20 offset:144
	global_store_dwordx4 v[18:19], v[2:5], off offset:48
	s_waitcnt lgkmcnt(1)
	s_nop 0
	v_cvt_pk_bf16_f32 v2, v6, v7
	v_cvt_pk_bf16_f32 v3, v8, v9
	s_waitcnt lgkmcnt(0)
	v_cvt_pk_bf16_f32 v4, v10, v11
	v_cvt_pk_bf16_f32 v5, v12, v13
	ds_read_b128 v[6:9], v20 offset:160
	ds_read_b128 v[10:13], v20 offset:176
	global_store_dwordx4 v[18:19], v[2:5], off offset:64
	s_waitcnt lgkmcnt(1)
	s_nop 0
	v_cvt_pk_bf16_f32 v2, v6, v7
	v_cvt_pk_bf16_f32 v3, v8, v9
	s_waitcnt lgkmcnt(0)
	v_cvt_pk_bf16_f32 v4, v10, v11
	v_cvt_pk_bf16_f32 v5, v12, v13
	ds_read_b128 v[6:9], v20 offset:192
	ds_read_b128 v[10:13], v20 offset:208
	global_store_dwordx4 v[18:19], v[2:5], off offset:80
	s_waitcnt lgkmcnt(1)
	s_nop 0
	v_cvt_pk_bf16_f32 v2, v6, v7
	v_cvt_pk_bf16_f32 v3, v8, v9
	s_waitcnt lgkmcnt(0)
	v_cvt_pk_bf16_f32 v4, v10, v11
	v_cvt_pk_bf16_f32 v5, v12, v13
	ds_read_b128 v[6:9], v20 offset:224
	global_store_dwordx4 v[18:19], v[2:5], off offset:96
	s_waitcnt lgkmcnt(0)
	s_nop 0
	v_cvt_pk_bf16_f32 v2, v6, v7
	v_cvt_pk_bf16_f32 v3, v8, v9
	v_cvt_pk_bf16_f32 v4, v14, v15
	v_cvt_pk_bf16_f32 v5, v16, v17
	global_store_dwordx4 v[18:19], v[2:5], off offset:112
	s_barrier
	s_cbranch_scc1 .LBB0_1120

;     ...
;   for (int kt = 0; kt < nk; ++kt) {
;     const int kn = (kt + 1 < nk) ? kt + 1 : kt;
;     GM_LOAD2(kn * 64, kn * bkstep)
;     __builtin_amdgcn_sched_barrier(0);
;     const char* As = smem + (kt & 1) * 2 * TILE_B;
;     const char* Bs = As + TILE_B;
;     if constexpr (HOIST) {
;       bf16x8 fa0[4], fa1[4], fb0[4], fb1[4];
; #pragma unroll
;       for (int st = 0; st < 4; ++st) {
;         fa0[st] = *(const bf16x8*)(As + aoff + st * 32);
;         fb0[st] = *(const bf16x8*)(Bs + boff + st * 32);
;         fa1[st] = *(const bf16x8*)(As + aoff + 32 * LSTR + st * 32);
;         fb1[st] = *(const bf16x8*)(Bs + boff + 32 * LSTR + st * 32);
;       }
;       __builtin_amdgcn_sched_barrier(0);
; #pragma unroll
;       for (int st = 0; st < 4; ++st) {
;         acc[0][0] = mfma32(fa0[st], fb0[st], acc[0][0]);
;         acc[0][1] = mfma32(fa0[st], fb1[st], acc[0][1]);
;         acc[1][0] = mfma32(fa1[st], fb0[st], acc[1][0]);
;         acc[1][1] = mfma32(fa1[st], fb1[st], acc[1][1]);
;       }
;     } else {
; #pragma unroll
;       for (int st = 0; st < 4; ++st) {
;         bf16x8 a0 = *(const bf16x8*)(As + aoff + st * 32);
;         bf16x8 a1 = *(const bf16x8*)(As + aoff + 32 * LSTR + st * 32);
;         bf16x8 b0 = *(const bf16x8*)(Bs + boff + st * 32);
;         bf16x8 b1 = *(const bf16x8*)(Bs + boff + 32 * LSTR + st * 32);
;         acc[0][0] = mfma32(a0, b0, acc[0][0]);
;         acc[0][1] = mfma32(a0, b1, acc[0][1]);
;         acc[1][0] = mfma32(a1, b0, acc[1][0]);
;         acc[1][1] = mfma32(a1, b1, acc[1][1]);
;       }
;     }
;     __builtin_amdgcn_sched_barrier(0);
;     {
;       char* Ad = smem + ((kt + 1) & 1) * 2 * TILE_B;
;       GM_STORE(Ad)
;     }
;     __syncthreads();
.LBB0_1401:
	s_and_b32 s26, s6, 2
	s_mulk_i32 s26, 0x4800
	v_add3_u32 v130, s26, v163, v164
	s_setprio 1
	v_add3_u32 v169, s26, v165, v164
	ds_read_b128 v[202:205], v130 offset:0
	ds_read_b128 v[206:209], v169 offset:18432
	ds_read_b128 v[214:217], v130 offset:4608
	ds_read_b128 v[210:213], v169 offset:23040
	s_waitcnt lgkmcnt(2)
	v_mfma_f32_32x32x16_bf16 v[50:65], v[202:205], v[206:209], v[50:65]
	ds_read_b128 v[218:221], v130 offset:32
	s_waitcnt lgkmcnt(2)
	v_mfma_f32_32x32x16_bf16 v[2:17], v[214:217], v[206:209], v[2:17]
	ds_read_b128 v[206:209], v169 offset:18464
	s_waitcnt lgkmcnt(2)
	v_mfma_f32_32x32x16_bf16 v[18:33], v[202:205], v[210:213], v[18:33]
	ds_read_b128 v[202:205], v130 offset:4640
	v_mfma_f32_32x32x16_bf16 v[34:49], v[214:217], v[210:213], v[34:49]
	ds_read_b128 v[210:213], v169 offset:23072
	s_waitcnt lgkmcnt(2)
	v_mfma_f32_32x32x16_bf16 v[50:65], v[218:221], v[206:209], v[50:65]
	ds_read_b128 v[214:217], v130 offset:64
	s_waitcnt lgkmcnt(2)
	v_mfma_f32_32x32x16_bf16 v[2:17], v[202:205], v[206:209], v[2:17]
	ds_read_b128 v[206:209], v169 offset:18496
	s_waitcnt lgkmcnt(2)
	v_mfma_f32_32x32x16_bf16 v[18:33], v[218:221], v[210:213], v[18:33]
	ds_read_b128 v[218:221], v130 offset:4672
	v_mfma_f32_32x32x16_bf16 v[34:49], v[202:205], v[210:213], v[34:49]
	ds_read_b128 v[210:213], v169 offset:23104
	s_waitcnt lgkmcnt(2)
	v_mfma_f32_32x32x16_bf16 v[50:65], v[214:217], v[206:209], v[50:65]
	ds_read_b128 v[202:205], v130 offset:96
	s_waitcnt lgkmcnt(2)
	v_mfma_f32_32x32x16_bf16 v[2:17], v[218:221], v[206:209], v[2:17]
	ds_read_b128 v[206:209], v169 offset:18528
	s_waitcnt lgkmcnt(2)
	v_mfma_f32_32x32x16_bf16 v[18:33], v[214:217], v[210:213], v[18:33]
	ds_read_b128 v[214:217], v130 offset:4704
	v_mfma_f32_32x32x16_bf16 v[34:49], v[218:221], v[210:213], v[34:49]
	ds_read_b128 v[210:213], v169 offset:23136
	s_waitcnt lgkmcnt(2)
	v_mfma_f32_32x32x16_bf16 v[50:65], v[202:205], v[206:209], v[50:65]
	s_waitcnt lgkmcnt(1)
	v_mfma_f32_32x32x16_bf16 v[2:17], v[214:217], v[206:209], v[2:17]
	s_waitcnt lgkmcnt(0)
	v_mfma_f32_32x32x16_bf16 v[18:33], v[202:205], v[210:213], v[18:33]
	v_mfma_f32_32x32x16_bf16 v[34:49], v[214:217], v[210:213], v[34:49]
	s_setprio 0
	s_add_i32 s6, s6, 2
	s_and_b32 s26, s6, 2
	s_add_u32 s10, s10, 0x80
	s_mulk_i32 s26, 0x4800
	s_addc_u32 s11, s11, 0
	v_add_u32_e32 v130, s26, v137
	s_cmpk_lg_i32 s10, 0x1f00
	s_waitcnt vmcnt(7)
	ds_write_b128 v130, v[170:173]
	v_lshl_add_u64 v[170:171], v[158:159], 0, s[10:11]
	v_add_co_u32_e32 v170, vcc, s18, v170
	s_nop 1
	v_addc_co_u32_e32 v171, vcc, 0, v171, vcc
	global_load_dwordx4 v[170:173], v[170:171], off offset:128
	s_waitcnt vmcnt(7)
	ds_write_b128 v130, v[174:177] offset:4608
	v_lshl_add_u64 v[174:175], v[158:159], 0, s[10:11]
	v_add_co_u32_e32 v174, vcc, s19, v174
	s_nop 1
	v_addc_co_u32_e32 v175, vcc, 0, v175, vcc
	global_load_dwordx4 v[174:177], v[174:175], off offset:128
	s_waitcnt vmcnt(7)
	ds_write_b128 v130, v[178:181] offset:9216
	v_lshl_add_u64 v[178:179], v[158:159], 0, s[10:11]
	v_add_co_u32_e32 v178, vcc, s20, v178
	s_nop 1
	v_addc_co_u32_e32 v179, vcc, 0, v179, vcc
	global_load_dwordx4 v[178:181], v[178:179], off offset:128
	s_waitcnt vmcnt(7)
	ds_write_b128 v130, v[182:185] offset:13824
	v_lshl_add_u64 v[182:183], v[158:159], 0, s[10:11]
	v_add_co_u32_e32 v182, vcc, s21, v182
	s_nop 1
	v_addc_co_u32_e32 v183, vcc, 0, v183, vcc
	global_load_dwordx4 v[182:185], v[182:183], off offset:128
	s_waitcnt vmcnt(7)
	ds_write_b128 v130, v[186:189] offset:18432
	v_lshl_add_u64 v[186:187], v[160:161], 0, s[10:11]
	v_add_co_u32_e32 v186, vcc, s22, v186
	s_nop 1
	v_addc_co_u32_e32 v187, vcc, 0, v187, vcc
	global_load_dwordx4 v[186:189], v[186:187], off offset:384
	s_waitcnt vmcnt(7)
	ds_write_b128 v130, v[190:193] offset:23040
	v_lshl_add_u64 v[190:191], v[160:161], 0, s[10:11]
	v_add_co_u32_e32 v190, vcc, s23, v190
	s_nop 1
	v_addc_co_u32_e32 v191, vcc, 0, v191, vcc
	global_load_dwordx4 v[190:193], v[190:191], off offset:384
	s_waitcnt vmcnt(7)
	ds_write_b128 v130, v[194:197] offset:27648
	v_lshl_add_u64 v[194:195], v[160:161], 0, s[10:11]
	v_add_co_u32_e32 v194, vcc, s24, v194
	s_nop 1
	v_addc_co_u32_e32 v195, vcc, 0, v195, vcc
	global_load_dwordx4 v[194:197], v[194:195], off offset:384
	s_waitcnt vmcnt(7)
	ds_write_b128 v130, v[198:201] offset:32256
	v_lshl_add_u64 v[198:199], v[160:161], 0, s[10:11]
	v_add_co_u32_e32 v198, vcc, s25, v198
	s_nop 1
	v_addc_co_u32_e32 v199, vcc, 0, v199, vcc
	global_load_dwordx4 v[198:201], v[198:199], off offset:384
	s_waitcnt lgkmcnt(0)
	s_barrier
	s_cbranch_scc1 .LBB0_1401
;     ...
;   for (int kt = 0; kt < nk; ++kt) {
;     const int kn = (kt + 1 < nk) ? kt + 1 : kt;
;     GM_LOAD2(kn * 64, kn * bkstep)
;     __builtin_amdgcn_sched_barrier(0);
;     const char* As = smem + (kt & 1) * 2 * TILE_B;
;     const char* Bs = As + TILE_B;
;     if constexpr (HOIST) {
;       bf16x8 fa0[4], fa1[4], fb0[4], fb1[4];
; #pragma unroll
;       for (int st = 0; st < 4; ++st) {
;         fa0[st] = *(const bf16x8*)(As + aoff + st * 32);
;         fb0[st] = *(const bf16x8*)(Bs + boff + st * 32);
;         fa1[st] = *(const bf16x8*)(As + aoff + 32 * LSTR + st * 32);
;         fb1[st] = *(const bf16x8*)(Bs + boff + 32 * LSTR + st * 32);
;       }
;       __builtin_amdgcn_sched_barrier(0);
; #pragma unroll
;       for (int st = 0; st < 4; ++st) {
;         acc[0][0] = mfma32(fa0[st], fb0[st], acc[0][0]);
;         acc[0][1] = mfma32(fa0[st], fb1[st], acc[0][1]);
;         acc[1][0] = mfma32(fa1[st], fb0[st], acc[1][0]);
;         acc[1][1] = mfma32(fa1[st], fb1[st], acc[1][1]);
;       }
;     } else {
; #pragma unroll
;       for (int st = 0; st < 4; ++st) {
;         bf16x8 a0 = *(const bf16x8*)(As + aoff + st * 32);
;         bf16x8 a1 = *(const bf16x8*)(As + aoff + 32 * LSTR + st * 32);
;         bf16x8 b0 = *(const bf16x8*)(Bs + boff + st * 32);
;         bf16x8 b1 = *(const bf16x8*)(Bs + boff + 32 * LSTR + st * 32);
;         acc[0][0] = mfma32(a0, b0, acc[0][0]);
;         acc[0][1] = mfma32(a0, b1, acc[0][1]);
;         acc[1][0] = mfma32(a1, b0, acc[1][0]);
;         acc[1][1] = mfma32(a1, b1, acc[1][1]);
;       }
;     }
;     __builtin_amdgcn_sched_barrier(0);
;     {
;       char* Ad = smem + ((kt + 1) & 1) * 2 * TILE_B;
;       GM_STORE(Ad)
;     }
;     __syncthreads();
	s_and_b32 s26, s6, 2
	s_mulk_i32 s26, 0x4800
	v_add3_u32 v130, s26, v163, v164
	s_setprio 1
	v_add3_u32 v169, s26, v165, v164
	ds_read_b128 v[202:205], v130 offset:0
	ds_read_b128 v[206:209], v169 offset:18432
	ds_read_b128 v[214:217], v130 offset:4608
	ds_read_b128 v[210:213], v169 offset:23040
	s_waitcnt lgkmcnt(2)
	v_mfma_f32_32x32x16_bf16 v[50:65], v[202:205], v[206:209], v[50:65]
	ds_read_b128 v[218:221], v130 offset:32
	s_waitcnt lgkmcnt(2)
	v_mfma_f32_32x32x16_bf16 v[2:17], v[214:217], v[206:209], v[2:17]
	ds_read_b128 v[206:209], v169 offset:18464
	s_waitcnt lgkmcnt(2)
	v_mfma_f32_32x32x16_bf16 v[18:33], v[202:205], v[210:213], v[18:33]
	ds_read_b128 v[202:205], v130 offset:4640
	v_mfma_f32_32x32x16_bf16 v[34:49], v[214:217], v[210:213], v[34:49]
	ds_read_b128 v[210:213], v169 offset:23072
	s_waitcnt lgkmcnt(2)
	v_mfma_f32_32x32x16_bf16 v[50:65], v[218:221], v[206:209], v[50:65]
	ds_read_b128 v[214:217], v130 offset:64
	s_waitcnt lgkmcnt(2)
	v_mfma_f32_32x32x16_bf16 v[2:17], v[202:205], v[206:209], v[2:17]
	ds_read_b128 v[206:209], v169 offset:18496
	s_waitcnt lgkmcnt(2)
	v_mfma_f32_32x32x16_bf16 v[18:33], v[218:221], v[210:213], v[18:33]
	ds_read_b128 v[218:221], v130 offset:4672
	v_mfma_f32_32x32x16_bf16 v[34:49], v[202:205], v[210:213], v[34:49]
	ds_read_b128 v[210:213], v169 offset:23104
	s_waitcnt lgkmcnt(2)
	v_mfma_f32_32x32x16_bf16 v[50:65], v[214:217], v[206:209], v[50:65]
	ds_read_b128 v[202:205], v130 offset:96
	s_waitcnt lgkmcnt(2)
	v_mfma_f32_32x32x16_bf16 v[2:17], v[218:221], v[206:209], v[2:17]
	ds_read_b128 v[206:209], v169 offset:18528
	s_waitcnt lgkmcnt(2)
	v_mfma_f32_32x32x16_bf16 v[18:33], v[214:217], v[210:213], v[18:33]
	ds_read_b128 v[214:217], v130 offset:4704
	v_mfma_f32_32x32x16_bf16 v[34:49], v[218:221], v[210:213], v[34:49]
	ds_read_b128 v[210:213], v169 offset:23136
	s_waitcnt lgkmcnt(2)
	v_mfma_f32_32x32x16_bf16 v[50:65], v[202:205], v[206:209], v[50:65]
	s_waitcnt lgkmcnt(1)
	v_mfma_f32_32x32x16_bf16 v[2:17], v[214:217], v[206:209], v[2:17]
	s_waitcnt lgkmcnt(0)
	v_mfma_f32_32x32x16_bf16 v[18:33], v[202:205], v[210:213], v[18:33]
	v_mfma_f32_32x32x16_bf16 v[34:49], v[214:217], v[210:213], v[34:49]
	s_setprio 0
	s_add_i32 s6, s6, 2
	s_and_b32 s26, s6, 2
	s_add_u32 s10, s10, 0x80
	s_mulk_i32 s26, 0x4800
	s_addc_u32 s11, s11, 0
	v_add_u32_e32 v130, s26, v137
	s_waitcnt vmcnt(7)
	ds_write_b128 v130, v[170:173]
	s_waitcnt vmcnt(6)
	ds_write_b128 v130, v[174:177] offset:4608
	s_waitcnt vmcnt(5)
	ds_write_b128 v130, v[178:181] offset:9216
	s_waitcnt vmcnt(4)
	ds_write_b128 v130, v[182:185] offset:13824
	s_waitcnt vmcnt(3)
	ds_write_b128 v130, v[186:189] offset:18432
	s_waitcnt vmcnt(2)
	ds_write_b128 v130, v[190:193] offset:23040
	s_waitcnt vmcnt(1)
	ds_write_b128 v130, v[194:197] offset:27648
	s_waitcnt vmcnt(0)
	ds_write_b128 v130, v[198:201] offset:32256
	s_waitcnt lgkmcnt(0)
	s_barrier
	v_lshl_add_u64 v[174:175], v[158:159], 0, s[10:11]
	v_add_co_u32_e32 v158, vcc, 0xdf00000, v174
	v_lshl_add_u64 v[190:191], v[160:161], 0, s[10:11]
	s_nop 0
	v_addc_co_u32_e32 v159, vcc, 0, v175, vcc
	v_add_co_u32_e32 v170, vcc, 0xdf80000, v174
	s_nop 1
	v_addc_co_u32_e32 v171, vcc, 0, v175, vcc
	v_add_co_u32_e32 v176, vcc, 0xe000000, v174
	s_nop 0
	v_addc_co_u32_e32 v177, vcc, 0, v175, vcc
	v_add_co_u32_e32 v178, vcc, 0xe080000, v174
	s_nop 1
	v_addc_co_u32_e32 v179, vcc, 0, v175, vcc
	v_add_co_u32_e32 v182, vcc, 0x35d31000, v190
	s_nop 0
	v_addc_co_u32_e32 v183, vcc, 0, v191, vcc
	v_add_co_u32_e32 v186, vcc, 0x35db1000, v190
	s_nop 1
	v_addc_co_u32_e32 v187, vcc, 0, v191, vcc
	v_add_co_u32_e32 v192, vcc, 0x35e31000, v190
	s_nop 0
	v_addc_co_u32_e32 v193, vcc, 0, v191, vcc
	v_add_co_u32_e32 v194, vcc, 0x35eb1000, v190
	s_nop 1
	v_addc_co_u32_e32 v195, vcc, 0, v191, vcc
	s_nop 0
	v_add3_u32 v130, s26, v163, v164
	s_setprio 1
	v_add3_u32 v169, s26, v165, v164
	ds_read_b128 v[198:201], v130 offset:0
	ds_read_b128 v[202:205], v169 offset:18432
	ds_read_b128 v[210:213], v130 offset:4608
	ds_read_b128 v[206:209], v169 offset:23040
	s_waitcnt lgkmcnt(2)
	v_mfma_f32_32x32x16_bf16 v[50:65], v[198:201], v[202:205], v[50:65]
	ds_read_b128 v[214:217], v130 offset:32
	s_waitcnt lgkmcnt(2)
	v_mfma_f32_32x32x16_bf16 v[2:17], v[210:213], v[202:205], v[2:17]
	ds_read_b128 v[202:205], v169 offset:18464
	s_waitcnt lgkmcnt(2)
	v_mfma_f32_32x32x16_bf16 v[18:33], v[198:201], v[206:209], v[18:33]
	ds_read_b128 v[198:201], v130 offset:4640
	v_mfma_f32_32x32x16_bf16 v[34:49], v[210:213], v[206:209], v[34:49]
	ds_read_b128 v[206:209], v169 offset:23072
	s_waitcnt lgkmcnt(2)
	v_mfma_f32_32x32x16_bf16 v[50:65], v[214:217], v[202:205], v[50:65]
	ds_read_b128 v[210:213], v130 offset:64
	s_waitcnt lgkmcnt(2)
	v_mfma_f32_32x32x16_bf16 v[2:17], v[198:201], v[202:205], v[2:17]
	ds_read_b128 v[202:205], v169 offset:18496
	s_waitcnt lgkmcnt(2)
	v_mfma_f32_32x32x16_bf16 v[18:33], v[214:217], v[206:209], v[18:33]
	ds_read_b128 v[214:217], v130 offset:4672
	v_mfma_f32_32x32x16_bf16 v[34:49], v[198:201], v[206:209], v[34:49]
	ds_read_b128 v[206:209], v169 offset:23104
	s_waitcnt lgkmcnt(2)
	v_mfma_f32_32x32x16_bf16 v[50:65], v[210:213], v[202:205], v[50:65]
	ds_read_b128 v[198:201], v130 offset:96
	s_waitcnt lgkmcnt(2)
	v_mfma_f32_32x32x16_bf16 v[2:17], v[214:217], v[202:205], v[2:17]
	ds_read_b128 v[202:205], v169 offset:18528
	s_waitcnt lgkmcnt(2)
	v_mfma_f32_32x32x16_bf16 v[18:33], v[210:213], v[206:209], v[18:33]
	ds_read_b128 v[210:213], v130 offset:4704
	v_mfma_f32_32x32x16_bf16 v[34:49], v[214:217], v[206:209], v[34:49]
	ds_read_b128 v[206:209], v169 offset:23136
	s_waitcnt lgkmcnt(2)
	v_mfma_f32_32x32x16_bf16 v[50:65], v[198:201], v[202:205], v[50:65]
	s_waitcnt lgkmcnt(1)
	v_mfma_f32_32x32x16_bf16 v[2:17], v[210:213], v[202:205], v[2:17]
	s_waitcnt lgkmcnt(0)
	v_mfma_f32_32x32x16_bf16 v[18:33], v[198:201], v[206:209], v[18:33]
	v_mfma_f32_32x32x16_bf16 v[34:49], v[210:213], v[206:209], v[34:49]
	s_setprio 0
	s_waitcnt lgkmcnt(0)
	s_barrier
; __device__ __forceinline__ void acc_to_lds(const f32x16 (&acc)[2][2], float* cs) {
;   const int tid = threadIdx.x, lane = tid & 63, wave = tid >> 6;
;   const int wm = wave >> 1, wn = wave & 1;
; #pragma unroll
;   for (int i = 0; i < 2; ++i)
; #pragma unroll
;     for (int j = 0; j < 2; ++j)
; #pragma unroll
;       for (int r = 0; r < 16; ++r) {
;         int row = wm * 64 + i * 32 + (r & 3) + 8 * (r >> 2) + 4 * (lane >> 5);
;         int col = wn * 64 + j * 32 + (lane & 31);
;         cs[row * CSTR + col] = acc[i][j][r];
;       }
;   __syncthreads();
; __device__ __forceinline__ void fourier_half_tile(const Params& P, bool isctx, int b, int mt, int nt, char* smem) {
;     ...
;       for (int q = 0; q < 8; ++q) {
;         float4 a = *(const float4*)(cs + r * CSTR + half * 64 + q * 8);
;         float4 c = *(const float4*)(cs + r * CSTR + half * 64 + q * 8 + 4);
;         uint4 o1, o2;
;         o1.x = pack2(pacc[q * 8 + 0] + a.x, pacc[q * 8 + 1] + a.y); o1.y = pack2(pacc[q * 8 + 2] + a.z, pacc[q * 8 + 3] + a.w);
;         o1.z = pack2(pacc[q * 8 + 4] + c.x, pacc[q * 8 + 5] + c.y); o1.w = pack2(pacc[q * 8 + 6] + c.z, pacc[q * 8 + 7] + c.w);
;         o2.x = pack2(pacc[q * 8 + 0] - a.x, pacc[q * 8 + 1] - a.y); o2.y = pack2(pacc[q * 8 + 2] - a.z, pacc[q * 8 + 3] - a.w);
;         o2.z = pack2(pacc[q * 8 + 4] - c.x, pacc[q * 8 + 5] - c.y); o2.w = pack2(pacc[q * 8 + 6] - c.z, pacc[q * 8 + 7] - c.w);
;         *(uint4*)(d1 + q * 8) = o1;
;         if (k > 0) *(uint4*)(d2 + q * 8) = o2;
	ds_write2_b32 v166, v50, v18 offset1:32
	ds_write2_b32 v166, v51, v19 offset0:132 offset1:164
	v_add_u32_e32 v18, 0x400, v166
	ds_write2_b32 v18, v52, v20 offset0:8 offset1:40
	ds_write2_b32 v18, v53, v21 offset0:140 offset1:172
	v_add_u32_e32 v18, 0x1000, v166
	ds_write2_b32 v18, v54, v22 offset0:32 offset1:64
	ds_write2_b32 v18, v55, v23 offset0:164 offset1:196
	v_add_u32_e32 v18, 0x1400, v166
	ds_write2_b32 v18, v56, v24 offset0:40 offset1:72
	ds_write2_b32 v18, v57, v25 offset0:172 offset1:204
	v_add_u32_e32 v18, 0x2000, v166
	ds_write2_b32 v18, v58, v26 offset0:64 offset1:96
	ds_write2_b32 v18, v59, v27 offset0:196 offset1:228
	v_add_u32_e32 v18, 0x2400, v166
	ds_write2_b32 v18, v60, v28 offset0:72 offset1:104
	ds_write2_b32 v18, v61, v29 offset0:204 offset1:236
	v_add_u32_e32 v18, 0x3000, v166
	ds_write2_b32 v18, v62, v30 offset0:96 offset1:128
	v_add_u32_e32 v18, 0x3200, v166
	ds_write2_b32 v18, v63, v31 offset0:100 offset1:132
	v_add_u32_e32 v18, 0x3400, v166
	ds_write2_b32 v18, v64, v32 offset0:104 offset1:136
	v_add_u32_e32 v18, 0x3600, v166
	ds_write2_b32 v18, v65, v33 offset0:108 offset1:140
	v_add_u32_e32 v18, 0x4000, v166
	ds_write2_b32 v18, v2, v34 offset0:128 offset1:160
	v_add_u32_e32 v2, 0x4400, v166
	ds_write2_b32 v2, v3, v35 offset0:4 offset1:36
	ds_write2_b32 v2, v4, v36 offset0:136 offset1:168
	v_add_u32_e32 v2, 0x4800, v166
	ds_write2_b32 v2, v5, v37 offset0:12 offset1:44
	v_add_u32_e32 v2, 0x5000, v166
	ds_write2_b32 v2, v6, v38 offset0:160 offset1:192
	v_add_u32_e32 v2, 0x5400, v166
	ds_write2_b32 v2, v7, v39 offset0:36 offset1:68
	ds_write2_b32 v2, v8, v40 offset0:168 offset1:200
	v_add_u32_e32 v2, 0x5800, v166
	ds_write2_b32 v2, v9, v41 offset0:44 offset1:76
	v_add_u32_e32 v2, 0x6000, v166
	ds_write2_b32 v2, v10, v42 offset0:192 offset1:224
	v_add_u32_e32 v2, 0x6400, v166
	ds_write2_b32 v2, v11, v43 offset0:68 offset1:100
	ds_write2_b32 v2, v12, v44 offset0:200 offset1:232
	v_add_u32_e32 v2, 0x6800, v166
	ds_write2_b32 v2, v13, v45 offset0:76 offset1:108
	v_add_u32_e32 v2, 0x7200, v166
	ds_write2_b32 v2, v14, v46 offset0:96 offset1:128
	v_add_u32_e32 v2, 0x7400, v166
	ds_write2_b32 v2, v15, v47 offset0:100 offset1:132
	v_add_u32_e32 v2, 0x7600, v166
	ds_write2_b32 v2, v16, v48 offset0:104 offset1:136
	v_add_u32_e32 v2, 0x7800, v166
	s_mov_b64 s[10:11], -1
	s_and_b64 vcc, exec, s[8:9]
	ds_write2_b32 v2, v17, v49 offset0:108 offset1:140
	s_waitcnt lgkmcnt(0)
	s_barrier
	s_cbranch_vccz .LBB0_1420
	ds_read_b128 v[2:5], v167
	ds_read_b128 v[6:9], v167 offset:16
	s_waitcnt lgkmcnt(1)
	v_add_f32_e32 v10, v78, v2
	v_add_f32_e32 v11, v79, v3
	v_sub_f32_e32 v2, v78, v2
	v_sub_f32_e32 v3, v79, v3
	v_add_f32_e32 v12, v80, v4
	v_add_f32_e32 v13, v81, v5
	v_cvt_pk_bf16_f32 v2, v2, v3
	v_sub_f32_e32 v3, v80, v4
	v_sub_f32_e32 v4, v81, v5
	v_cvt_pk_bf16_f32 v10, v10, v11
	v_cvt_pk_bf16_f32 v11, v12, v13
	s_waitcnt lgkmcnt(0)
	v_add_f32_e32 v12, v74, v6
	v_add_f32_e32 v13, v75, v7
	v_cvt_pk_bf16_f32 v3, v3, v4
	v_sub_f32_e32 v4, v74, v6
	v_sub_f32_e32 v5, v75, v7
	v_cvt_pk_bf16_f32 v12, v12, v13
	v_add_f32_e32 v13, v76, v8
	v_cvt_pk_bf16_f32 v4, v4, v5
	v_sub_f32_e32 v5, v76, v8
	v_add_f32_e32 v14, v77, v9
	v_cvt_pk_bf16_f32 v13, v13, v14
	v_sub_f32_e32 v6, v77, v9
	v_cvt_pk_bf16_f32 v5, v5, v6
	global_store_dwordx4 v[148:149], v[10:13], off
	s_and_saveexec_b64 s[10:11], s[2:3]
	s_cbranch_execz .LBB0_1405
	global_store_dwordx4 v[150:151], v[2:5], off

;     ...
;   for (int kt = 0; kt < nk; ++kt) {
;     const int kn = (kt + 1 < nk) ? kt + 1 : kt;
;     GM_LOAD2(kn * 64, kn * bkstep)
;     __builtin_amdgcn_sched_barrier(0);
;     const char* As = smem + (kt & 1) * 2 * TILE_B;
;     const char* Bs = As + TILE_B;
;     if constexpr (HOIST) {
;       bf16x8 fa0[4], fa1[4], fb0[4], fb1[4];
; #pragma unroll
;       for (int st = 0; st < 4; ++st) {
;         fa0[st] = *(const bf16x8*)(As + aoff + st * 32);
;         fb0[st] = *(const bf16x8*)(Bs + boff + st * 32);
;         fa1[st] = *(const bf16x8*)(As + aoff + 32 * LSTR + st * 32);
;         fb1[st] = *(const bf16x8*)(Bs + boff + 32 * LSTR + st * 32);
;       }
;       __builtin_amdgcn_sched_barrier(0);
; #pragma unroll
;       for (int st = 0; st < 4; ++st) {
;         acc[0][0] = mfma32(fa0[st], fb0[st], acc[0][0]);
;         acc[0][1] = mfma32(fa0[st], fb1[st], acc[0][1]);
;         acc[1][0] = mfma32(fa1[st], fb0[st], acc[1][0]);
;         acc[1][1] = mfma32(fa1[st], fb1[st], acc[1][1]);
;       }
;     } else {
; #pragma unroll
;       for (int st = 0; st < 4; ++st) {
;         bf16x8 a0 = *(const bf16x8*)(As + aoff + st * 32);
;         bf16x8 a1 = *(const bf16x8*)(As + aoff + 32 * LSTR + st * 32);
;         bf16x8 b0 = *(const bf16x8*)(Bs + boff + st * 32);
;         bf16x8 b1 = *(const bf16x8*)(Bs + boff + 32 * LSTR + st * 32);
;         acc[0][0] = mfma32(a0, b0, acc[0][0]);
;         acc[0][1] = mfma32(a0, b1, acc[0][1]);
;         acc[1][0] = mfma32(a1, b0, acc[1][0]);
;         acc[1][1] = mfma32(a1, b1, acc[1][1]);
;       }
;     }
;     __builtin_amdgcn_sched_barrier(0);
;     {
;       char* Ad = smem + ((kt + 1) & 1) * 2 * TILE_B;
;       GM_STORE(Ad)
;     }
;     __syncthreads();
.LBB0_1640:
	s_and_b32 s40, s39, 2
	s_mulk_i32 s40, 0x4800
	v_add3_u32 v220, s40, v137, v164
	s_setprio 1
	v_add3_u32 v221, s40, v165, v164
	ds_read_b128 v[200:203], v220 offset:0
	ds_read_b128 v[204:207], v221 offset:18432
	ds_read_b128 v[212:215], v220 offset:4608
	ds_read_b128 v[208:211], v221 offset:23040
	s_waitcnt lgkmcnt(2)
	v_mfma_f32_32x32x16_bf16 v[34:49], v[200:203], v[204:207], v[34:49]
	ds_read_b128 v[216:219], v220 offset:32
	s_waitcnt lgkmcnt(2)
	v_mfma_f32_32x32x16_bf16 v[18:33], v[212:215], v[204:207], v[18:33]
	ds_read_b128 v[204:207], v221 offset:18464
	s_waitcnt lgkmcnt(2)
	v_mfma_f32_32x32x16_bf16 v[2:17], v[200:203], v[208:211], v[2:17]
	ds_read_b128 v[200:203], v220 offset:4640
	v_mfma_f32_32x32x16_bf16 v[50:65], v[212:215], v[208:211], v[50:65]
	ds_read_b128 v[208:211], v221 offset:23072
	s_waitcnt lgkmcnt(2)
	v_mfma_f32_32x32x16_bf16 v[34:49], v[216:219], v[204:207], v[34:49]
	ds_read_b128 v[212:215], v220 offset:64
	s_waitcnt lgkmcnt(2)
	v_mfma_f32_32x32x16_bf16 v[18:33], v[200:203], v[204:207], v[18:33]
	ds_read_b128 v[204:207], v221 offset:18496
	s_waitcnt lgkmcnt(2)
	v_mfma_f32_32x32x16_bf16 v[2:17], v[216:219], v[208:211], v[2:17]
	ds_read_b128 v[216:219], v220 offset:4672
	v_mfma_f32_32x32x16_bf16 v[50:65], v[200:203], v[208:211], v[50:65]
	ds_read_b128 v[208:211], v221 offset:23104
	s_waitcnt lgkmcnt(2)
	v_mfma_f32_32x32x16_bf16 v[34:49], v[212:215], v[204:207], v[34:49]
	ds_read_b128 v[200:203], v220 offset:96
	s_waitcnt lgkmcnt(2)
	v_mfma_f32_32x32x16_bf16 v[18:33], v[216:219], v[204:207], v[18:33]
	ds_read_b128 v[204:207], v221 offset:18528
	s_waitcnt lgkmcnt(2)
	v_mfma_f32_32x32x16_bf16 v[2:17], v[212:215], v[208:211], v[2:17]
	ds_read_b128 v[212:215], v220 offset:4704
	v_mfma_f32_32x32x16_bf16 v[50:65], v[216:219], v[208:211], v[50:65]
	ds_read_b128 v[208:211], v221 offset:23136
	s_waitcnt lgkmcnt(2)
	v_mfma_f32_32x32x16_bf16 v[34:49], v[200:203], v[204:207], v[34:49]
	s_waitcnt lgkmcnt(1)
	v_mfma_f32_32x32x16_bf16 v[18:33], v[212:215], v[204:207], v[18:33]
	s_waitcnt lgkmcnt(0)
	v_mfma_f32_32x32x16_bf16 v[2:17], v[200:203], v[208:211], v[2:17]
	v_mfma_f32_32x32x16_bf16 v[50:65], v[212:215], v[208:211], v[50:65]
	s_setprio 0
	s_add_i32 s39, s39, 2
	s_and_b32 s40, s39, 2
	s_mulk_i32 s40, 0x4800
	s_add_i32 s6, s6, -1
	v_add_u32_e32 v200, s40, v135
	v_lshl_add_u64 v[148:149], v[148:149], 0, s[8:9]
	v_lshl_add_u64 v[150:151], v[150:151], 0, s[8:9]
	v_lshl_add_u64 v[152:153], v[152:153], 0, s[8:9]
	v_lshl_add_u64 v[154:155], v[154:155], 0, s[8:9]
	v_lshl_add_u64 v[156:157], v[156:157], 0, s[8:9]
	v_lshl_add_u64 v[158:159], v[158:159], 0, s[8:9]
	v_lshl_add_u64 v[160:161], v[160:161], 0, s[8:9]
	v_lshl_add_u64 v[162:163], v[162:163], 0, s[8:9]
	s_cmp_lg_u32 s6, 0
	s_waitcnt vmcnt(7)
	ds_write_b128 v200, v[168:171]
	v_lshl_add_u64 v[168:169], v[148:149], 0, v[68:69]
	global_load_dwordx4 v[168:171], v[168:169], off offset:128
	s_waitcnt vmcnt(7)
	ds_write_b128 v200, v[172:175] offset:4608
	v_lshl_add_u64 v[172:173], v[150:151], 0, v[68:69]
	global_load_dwordx4 v[172:175], v[172:173], off offset:128
	s_waitcnt vmcnt(7)
	ds_write_b128 v200, v[176:179] offset:9216
	v_lshl_add_u64 v[176:177], v[152:153], 0, v[68:69]
	global_load_dwordx4 v[176:179], v[176:177], off offset:128
	s_waitcnt vmcnt(7)
	ds_write_b128 v200, v[180:183] offset:13824
	v_lshl_add_u64 v[180:181], v[154:155], 0, v[68:69]
	global_load_dwordx4 v[180:183], v[180:181], off offset:128
	s_waitcnt vmcnt(7)
	ds_write_b128 v200, v[184:187] offset:18432
	v_lshl_add_u64 v[184:185], v[156:157], 0, v[68:69]
	global_load_dwordx4 v[184:187], v[184:185], off offset:128
	s_waitcnt vmcnt(7)
	ds_write_b128 v200, v[188:191] offset:23040
	v_lshl_add_u64 v[188:189], v[158:159], 0, v[68:69]
	global_load_dwordx4 v[188:191], v[188:189], off offset:128
	s_waitcnt vmcnt(7)
	ds_write_b128 v200, v[192:195] offset:27648
	v_lshl_add_u64 v[192:193], v[160:161], 0, v[68:69]
	global_load_dwordx4 v[192:195], v[192:193], off offset:128
	s_waitcnt vmcnt(7)
	ds_write_b128 v200, v[196:199] offset:32256
	v_lshl_add_u64 v[196:197], v[162:163], 0, v[68:69]
	global_load_dwordx4 v[196:199], v[196:197], off offset:128
	s_waitcnt lgkmcnt(0)
	s_barrier
	s_cbranch_scc1 .LBB0_1640
	s_and_b32 s40, s39, 2
	s_mulk_i32 s40, 0x4800
	v_add3_u32 v220, s40, v137, v164
	s_setprio 1
	v_add3_u32 v221, s40, v165, v164
	ds_read_b128 v[200:203], v220 offset:0
	ds_read_b128 v[204:207], v221 offset:18432
	ds_read_b128 v[212:215], v220 offset:4608
	ds_read_b128 v[208:211], v221 offset:23040
	s_waitcnt lgkmcnt(2)
	v_mfma_f32_32x32x16_bf16 v[34:49], v[200:203], v[204:207], v[34:49]
	ds_read_b128 v[216:219], v220 offset:32
	s_waitcnt lgkmcnt(2)
	v_mfma_f32_32x32x16_bf16 v[18:33], v[212:215], v[204:207], v[18:33]
	ds_read_b128 v[204:207], v221 offset:18464
	s_waitcnt lgkmcnt(2)
	v_mfma_f32_32x32x16_bf16 v[2:17], v[200:203], v[208:211], v[2:17]
	ds_read_b128 v[200:203], v220 offset:4640
	v_mfma_f32_32x32x16_bf16 v[50:65], v[212:215], v[208:211], v[50:65]
	ds_read_b128 v[208:211], v221 offset:23072
	s_waitcnt lgkmcnt(2)
	v_mfma_f32_32x32x16_bf16 v[34:49], v[216:219], v[204:207], v[34:49]
	ds_read_b128 v[212:215], v220 offset:64
	s_waitcnt lgkmcnt(2)
	v_mfma_f32_32x32x16_bf16 v[18:33], v[200:203], v[204:207], v[18:33]
	ds_read_b128 v[204:207], v221 offset:18496
	s_waitcnt lgkmcnt(2)
	v_mfma_f32_32x32x16_bf16 v[2:17], v[216:219], v[208:211], v[2:17]
	ds_read_b128 v[216:219], v220 offset:4672
	v_mfma_f32_32x32x16_bf16 v[50:65], v[200:203], v[208:211], v[50:65]
	ds_read_b128 v[208:211], v221 offset:23104
	s_waitcnt lgkmcnt(2)
	v_mfma_f32_32x32x16_bf16 v[34:49], v[212:215], v[204:207], v[34:49]
	ds_read_b128 v[200:203], v220 offset:96
	s_waitcnt lgkmcnt(2)
;     ...
;         acc[0][0] = mfma32(fa0[st], fb0[st], acc[0][0]);
;         acc[0][1] = mfma32(fa0[st], fb1[st], acc[0][1]);
;         acc[1][0] = mfma32(fa1[st], fb0[st], acc[1][0]);
;         acc[1][1] = mfma32(fa1[st], fb1[st], acc[1][1]);
;       }
;     } else {
; #pragma unroll
;       for (int st = 0; st < 4; ++st) {
;         bf16x8 a0 = *(const bf16x8*)(As + aoff + st * 32);
;         bf16x8 a1 = *(const bf16x8*)(As + aoff + 32 * LSTR + st * 32);
;         bf16x8 b0 = *(const bf16x8*)(Bs + boff + st * 32);
;         bf16x8 b1 = *(const bf16x8*)(Bs + boff + 32 * LSTR + st * 32);
;         acc[0][0] = mfma32(a0, b0, acc[0][0]);
;         acc[0][1] = mfma32(a0, b1, acc[0][1]);
;         acc[1][0] = mfma32(a1, b0, acc[1][0]);
;         acc[1][1] = mfma32(a1, b1, acc[1][1]);
;       }
;     }
;     __builtin_amdgcn_sched_barrier(0);
;     {
;       char* Ad = smem + ((kt + 1) & 1) * 2 * TILE_B;
;       GM_STORE(Ad)
;     }
;     __syncthreads();
; __device__ __forceinline__ void acc_to_lds(const f32x16 (&acc)[2][2], float* cs) {
;     ...
;       for (int r = 0; r < 16; ++r) {
;         int row = wm * 64 + i * 32 + (r & 3) + 8 * (r >> 2) + 4 * (lane >> 5);
;         int col = wn * 64 + j * 32 + (lane & 31);
;         cs[row * CSTR + col] = acc[i][j][r];
;       }
;   __syncthreads();
; __device__ __forceinline__ void merge_tile(const Params& P, int l, int mt, int nt, char* smem) {
;     ...
;     const u16* gp = WSP(u16, OFF_G) + grow * 3072 + br * 1024 + nt * 128 + half * 64;
	v_mfma_f32_32x32x16_bf16 v[18:33], v[216:219], v[204:207], v[18:33]
	ds_read_b128 v[204:207], v221 offset:18528
	s_waitcnt lgkmcnt(2)
	v_mfma_f32_32x32x16_bf16 v[2:17], v[212:215], v[208:211], v[2:17]
	ds_read_b128 v[212:215], v220 offset:4704
	v_mfma_f32_32x32x16_bf16 v[50:65], v[216:219], v[208:211], v[50:65]
	ds_read_b128 v[208:211], v221 offset:23136
	s_waitcnt lgkmcnt(2)
	v_mfma_f32_32x32x16_bf16 v[34:49], v[200:203], v[204:207], v[34:49]
	s_waitcnt lgkmcnt(1)
	v_mfma_f32_32x32x16_bf16 v[18:33], v[212:215], v[204:207], v[18:33]
	s_waitcnt lgkmcnt(0)
	v_mfma_f32_32x32x16_bf16 v[2:17], v[200:203], v[208:211], v[2:17]
	v_mfma_f32_32x32x16_bf16 v[50:65], v[212:215], v[208:211], v[50:65]
	s_setprio 0
	s_add_i32 s39, s39, 2
	s_and_b32 s40, s39, 2
	s_mulk_i32 s40, 0x4800
	v_add_u32_e32 v200, s40, v135
	v_lshl_add_u64 v[148:149], v[148:149], 0, s[8:9]
	v_lshl_add_u64 v[150:151], v[150:151], 0, s[8:9]
	v_lshl_add_u64 v[152:153], v[152:153], 0, s[8:9]
	v_lshl_add_u64 v[154:155], v[154:155], 0, s[8:9]
	v_lshl_add_u64 v[156:157], v[156:157], 0, s[8:9]
	v_lshl_add_u64 v[158:159], v[158:159], 0, s[8:9]
	v_lshl_add_u64 v[160:161], v[160:161], 0, s[8:9]
	v_lshl_add_u64 v[162:163], v[162:163], 0, s[8:9]
	s_waitcnt vmcnt(7)
	ds_write_b128 v200, v[168:171]
	s_waitcnt vmcnt(6)
	ds_write_b128 v200, v[172:175] offset:4608
	s_waitcnt vmcnt(5)
	ds_write_b128 v200, v[176:179] offset:9216
	s_waitcnt vmcnt(4)
	ds_write_b128 v200, v[180:183] offset:13824
	s_waitcnt vmcnt(3)
	ds_write_b128 v200, v[184:187] offset:18432
	s_waitcnt vmcnt(2)
	ds_write_b128 v200, v[188:191] offset:23040
	s_waitcnt vmcnt(1)
	ds_write_b128 v200, v[192:195] offset:27648
	s_waitcnt vmcnt(0)
	ds_write_b128 v200, v[196:199] offset:32256
	s_waitcnt lgkmcnt(0)
	s_barrier
	v_lshl_add_u64 v[180:181], v[162:163], 0, v[68:69]
	v_lshl_add_u64 v[176:177], v[160:161], 0, v[68:69]
	v_lshl_add_u64 v[172:173], v[158:159], 0, v[68:69]
	v_lshl_add_u64 v[168:169], v[156:157], 0, v[68:69]
	v_lshl_add_u64 v[160:161], v[154:155], 0, v[68:69]
	v_lshl_add_u64 v[156:157], v[152:153], 0, v[68:69]
	v_lshl_add_u64 v[152:153], v[150:151], 0, v[68:69]
	v_lshl_add_u64 v[148:149], v[148:149], 0, v[68:69]
	s_nop 0
	s_nop 0
	s_nop 0
	s_nop 0
	s_nop 0
	s_nop 0
	s_nop 0
	v_add3_u32 v68, s40, v137, v164
	s_setprio 1
	v_add3_u32 v212, s40, v165, v164
	ds_read_b128 v[184:187], v68 offset:0
	ds_read_b128 v[188:191], v212 offset:18432
	ds_read_b128 v[196:199], v68 offset:4608
	ds_read_b128 v[192:195], v212 offset:23040
	s_waitcnt lgkmcnt(2)
	v_mfma_f32_32x32x16_bf16 v[34:49], v[184:187], v[188:191], v[34:49]
	ds_read_b128 v[200:203], v68 offset:32
	s_waitcnt lgkmcnt(2)
	v_mfma_f32_32x32x16_bf16 v[18:33], v[196:199], v[188:191], v[18:33]
	ds_read_b128 v[188:191], v212 offset:18464
	s_waitcnt lgkmcnt(2)
	v_mfma_f32_32x32x16_bf16 v[2:17], v[184:187], v[192:195], v[2:17]
	ds_read_b128 v[184:187], v68 offset:4640
	v_mfma_f32_32x32x16_bf16 v[50:65], v[196:199], v[192:195], v[50:65]
	ds_read_b128 v[192:195], v212 offset:23072
	s_waitcnt lgkmcnt(2)
	v_mfma_f32_32x32x16_bf16 v[34:49], v[200:203], v[188:191], v[34:49]
	ds_read_b128 v[196:199], v68 offset:64
	s_waitcnt lgkmcnt(2)
	v_mfma_f32_32x32x16_bf16 v[18:33], v[184:187], v[188:191], v[18:33]
	ds_read_b128 v[188:191], v212 offset:18496
	s_waitcnt lgkmcnt(2)
	v_mfma_f32_32x32x16_bf16 v[2:17], v[200:203], v[192:195], v[2:17]
	ds_read_b128 v[200:203], v68 offset:4672
	v_mfma_f32_32x32x16_bf16 v[50:65], v[184:187], v[192:195], v[50:65]
	ds_read_b128 v[192:195], v212 offset:23104
	s_waitcnt lgkmcnt(2)
	v_mfma_f32_32x32x16_bf16 v[34:49], v[196:199], v[188:191], v[34:49]
	ds_read_b128 v[184:187], v68 offset:96
	s_waitcnt lgkmcnt(2)
	v_mfma_f32_32x32x16_bf16 v[18:33], v[200:203], v[188:191], v[18:33]
	ds_read_b128 v[188:191], v212 offset:18528
	s_waitcnt lgkmcnt(2)
	v_mfma_f32_32x32x16_bf16 v[2:17], v[196:199], v[192:195], v[2:17]
	ds_read_b128 v[196:199], v68 offset:4704
	v_mfma_f32_32x32x16_bf16 v[50:65], v[200:203], v[192:195], v[50:65]
	ds_read_b128 v[192:195], v212 offset:23136
	s_waitcnt lgkmcnt(2)
	v_mfma_f32_32x32x16_bf16 v[34:49], v[184:187], v[188:191], v[34:49]
	s_waitcnt lgkmcnt(1)
	v_mfma_f32_32x32x16_bf16 v[18:33], v[196:199], v[188:191], v[18:33]
	s_waitcnt lgkmcnt(0)
	v_mfma_f32_32x32x16_bf16 v[2:17], v[184:187], v[192:195], v[2:17]
	v_mfma_f32_32x32x16_bf16 v[50:65], v[196:199], v[192:195], v[50:65]
	s_setprio 0
	s_waitcnt lgkmcnt(0)
	s_barrier
	ds_write2_b32 v166, v34, v2 offset1:32
	ds_write2_b32 v166, v35, v3 offset0:132 offset1:164
	v_add_u32_e32 v2, 0x400, v166
	ds_write2_b32 v2, v36, v4 offset0:8 offset1:40
	ds_write2_b32 v2, v37, v5 offset0:140 offset1:172
	v_add_u32_e32 v2, 0x1000, v166
	ds_write2_b32 v2, v38, v6 offset0:32 offset1:64
	ds_write2_b32 v2, v39, v7 offset0:164 offset1:196
	v_add_u32_e32 v2, 0x1400, v166
	ds_write2_b32 v2, v40, v8 offset0:40 offset1:72
	ds_write2_b32 v2, v41, v9 offset0:172 offset1:204
	v_add_u32_e32 v2, 0x2000, v166
	ds_write2_b32 v2, v42, v10 offset0:64 offset1:96
	ds_write2_b32 v2, v43, v11 offset0:196 offset1:228
	v_add_u32_e32 v2, 0x2400, v166
	ds_write2_b32 v2, v44, v12 offset0:72 offset1:104
	ds_write2_b32 v2, v45, v13 offset0:204 offset1:236
	v_add_u32_e32 v2, 0x3000, v166
	ds_write2_b32 v2, v46, v14 offset0:96 offset1:128
	v_add_u32_e32 v2, 0x3200, v166
	ds_write2_b32 v2, v47, v15 offset0:100 offset1:132
	v_add_u32_e32 v2, 0x3400, v166
	ds_write2_b32 v2, v48, v16 offset0:104 offset1:136
	v_add_u32_e32 v2, 0x3600, v166
	ds_write2_b32 v2, v49, v17 offset0:108 offset1:140
	v_add_u32_e32 v2, 0x4000, v166
	ds_write2_b32 v2, v18, v50 offset0:128 offset1:160
	v_add_u32_e32 v2, 0x4400, v166
	ds_write2_b32 v2, v19, v51 offset0:4 offset1:36
	ds_write2_b32 v2, v20, v52 offset0:136 offset1:168
	v_add_u32_e32 v2, 0x4800, v166
	ds_write2_b32 v2, v21, v53 offset0:12 offset1:44
	v_add_u32_e32 v2, 0x5000, v166
	ds_write2_b32 v2, v22, v54 offset0:160 offset1:192
	v_add_u32_e32 v2, 0x5400, v166
	ds_write2_b32 v2, v23, v55 offset0:36 offset1:68
	ds_write2_b32 v2, v24, v56 offset0:168 offset1:200
	v_add_u32_e32 v2, 0x5800, v166
	ds_write2_b32 v2, v25, v57 offset0:44 offset1:76
	v_add_u32_e32 v2, 0x6000, v166
	ds_write2_b32 v2, v26, v58 offset0:192 offset1:224
	v_add_u32_e32 v2, 0x6400, v166
	ds_write2_b32 v2, v27, v59 offset0:68 offset1:100
	ds_write2_b32 v2, v28, v60 offset0:200 offset1:232
	v_add_u32_e32 v2, 0x6800, v166
	ds_write2_b32 v2, v29, v61 offset0:76 offset1:108
	v_add_u32_e32 v2, 0x7200, v166
	ds_write2_b32 v2, v30, v62 offset0:96 offset1:128
	v_add_u32_e32 v2, 0x7400, v166
	ds_write2_b32 v2, v31, v63 offset0:100 offset1:132
	v_add_u32_e32 v2, 0x7600, v166
	s_lshl_b32 s6, s38, 11
	ds_write2_b32 v2, v32, v64 offset0:104 offset1:136
	v_add_u32_e32 v2, 0x7800, v166
	v_lshl_add_u64 v[46:47], v[118:119], 0, s[6:7]
	ds_write2_b32 v2, v33, v65 offset0:108 offset1:140
	s_waitcnt lgkmcnt(0)
	s_barrier
; __device__ __forceinline__ void merge_tile(const Params& P, int l, int mt, int nt, char* smem) {
;     ...
;     const u16* gp = WSP(u16, OFF_G) + grow * 3072 + br * 1024 + nt * 128 + half * 64;
; #pragma unroll
;     for (int q = 0; q < 8; ++q) {
;       uint4 gq = *(const uint4*)(gp + q * 8);
;       float4 a = *(const float4*)(cs + r * CSTR + half * 64 + q * 8);
;       float4 c = *(const float4*)(cs + r * CSTR + half * 64 + q * 8 + 4);
;       macc[q * 8 + 0] += __uint_as_float(gq.x << 16) * a.x;
;       macc[q * 8 + 1] += __uint_as_float(gq.x & 0xffff0000u) * a.y;
;       macc[q * 8 + 2] += __uint_as_float(gq.y << 16) * a.z;
;       macc[q * 8 + 3] += __uint_as_float(gq.y & 0xffff0000u) * a.w;
;       macc[q * 8 + 4] += __uint_as_float(gq.z << 16) * c.x;
;       macc[q * 8 + 5] += __uint_as_float(gq.z & 0xffff0000u) * c.y;
;       macc[q * 8 + 6] += __uint_as_float(gq.w << 16) * c.z;
;       macc[q * 8 + 7] += __uint_as_float(gq.w & 0xffff0000u) * c.w;
;     }
;     __syncthreads();
	global_load_dwordx4 v[2:5], v[46:47], off
	global_load_dwordx4 v[6:9], v[46:47], off offset:16
	global_load_dwordx4 v[10:13], v[46:47], off offset:32
	global_load_dwordx4 v[14:17], v[46:47], off offset:48
	global_load_dwordx4 v[18:21], v[46:47], off offset:64
	global_load_dwordx4 v[22:25], v[46:47], off offset:80
	ds_read_b128 v[26:29], v167
	ds_read_b128 v[30:33], v167 offset:16
	ds_read_b128 v[34:37], v167 offset:32
	ds_read_b128 v[38:41], v167 offset:48
	global_load_dwordx4 v[42:45], v[46:47], off offset:112
	s_nop 0
	global_load_dwordx4 v[46:49], v[46:47], off offset:96
	s_add_i32 s38, s38, 1
	s_cmp_lg_u32 s38, 3
	s_waitcnt vmcnt(7)
	v_lshlrev_b32_e32 v50, 16, v2
	v_and_b32_e32 v51, 0xffff0000, v2
	v_lshlrev_b32_e32 v2, 16, v3
	v_and_b32_e32 v3, 0xffff0000, v3
	s_waitcnt lgkmcnt(3)
	v_pk_fma_f32 v[144:145], v[28:29], v[2:3], v[144:145]
	v_lshlrev_b32_e32 v2, 16, v4
	v_and_b32_e32 v3, 0xffff0000, v4
	s_waitcnt lgkmcnt(2)
	v_pk_fma_f32 v[142:143], v[30:31], v[2:3], v[142:143]
	v_lshlrev_b32_e32 v2, 16, v5
	v_and_b32_e32 v3, 0xffff0000, v5
	v_pk_fma_f32 v[140:141], v[32:33], v[2:3], v[140:141]
	s_waitcnt vmcnt(6)
	v_lshlrev_b32_e32 v2, 16, v6
	v_and_b32_e32 v3, 0xffff0000, v6
	s_waitcnt lgkmcnt(1)
	v_pk_fma_f32 v[138:139], v[34:35], v[2:3], v[138:139]
	v_lshlrev_b32_e32 v2, 16, v7
	v_and_b32_e32 v3, 0xffff0000, v7
	v_pk_fma_f32 v[132:133], v[36:37], v[2:3], v[132:133]
	v_lshlrev_b32_e32 v2, 16, v8
	v_and_b32_e32 v3, 0xffff0000, v8
	s_waitcnt lgkmcnt(0)
	v_pk_fma_f32 v[130:131], v[38:39], v[2:3], v[130:131]
	ds_read_b128 v[2:5], v167 offset:64
	v_lshlrev_b32_e32 v6, 16, v9
	v_and_b32_e32 v7, 0xffff0000, v9
	v_pk_fma_f32 v[128:129], v[40:41], v[6:7], v[128:129]
	ds_read_b128 v[6:9], v167 offset:80
	v_pk_fma_f32 v[146:147], v[26:27], v[50:51], v[146:147]
	s_waitcnt vmcnt(5)
	v_lshlrev_b32_e32 v26, 16, v10
	v_and_b32_e32 v27, 0xffff0000, v10
	s_waitcnt lgkmcnt(1)
	v_pk_fma_f32 v[126:127], v[2:3], v[26:27], v[126:127]
	v_lshlrev_b32_e32 v2, 16, v11
	v_and_b32_e32 v3, 0xffff0000, v11
	v_pk_fma_f32 v[124:125], v[4:5], v[2:3], v[124:125]
	v_lshlrev_b32_e32 v2, 16, v12
	v_and_b32_e32 v3, 0xffff0000, v12
	s_waitcnt lgkmcnt(0)
	v_pk_fma_f32 v[122:123], v[6:7], v[2:3], v[122:123]
	ds_read_b128 v[2:5], v167 offset:96
	v_lshlrev_b32_e32 v6, 16, v13
	v_and_b32_e32 v7, 0xffff0000, v13
	v_pk_fma_f32 v[120:121], v[8:9], v[6:7], v[120:121]
	ds_read_b128 v[6:9], v167 offset:112
	s_waitcnt vmcnt(4)
	v_lshlrev_b32_e32 v10, 16, v14
	v_and_b32_e32 v11, 0xffff0000, v14
	s_waitcnt lgkmcnt(1)
	v_pk_fma_f32 v[116:117], v[2:3], v[10:11], v[116:117]
	v_lshlrev_b32_e32 v2, 16, v15
	v_and_b32_e32 v3, 0xffff0000, v15
	v_pk_fma_f32 v[114:115], v[4:5], v[2:3], v[114:115]
	v_lshlrev_b32_e32 v2, 16, v16
	v_and_b32_e32 v3, 0xffff0000, v16
	s_waitcnt lgkmcnt(0)
	v_pk_fma_f32 v[112:113], v[6:7], v[2:3], v[112:113]
	ds_read_b128 v[2:5], v167 offset:128
	v_lshlrev_b32_e32 v6, 16, v17
	v_and_b32_e32 v7, 0xffff0000, v17
	v_pk_fma_f32 v[110:111], v[8:9], v[6:7], v[110:111]
	ds_read_b128 v[6:9], v167 offset:144
	s_waitcnt vmcnt(3)
	v_lshlrev_b32_e32 v10, 16, v18
	v_and_b32_e32 v11, 0xffff0000, v18
	s_waitcnt lgkmcnt(1)
	v_pk_fma_f32 v[106:107], v[2:3], v[10:11], v[106:107]
	v_lshlrev_b32_e32 v2, 16, v19
	v_and_b32_e32 v3, 0xffff0000, v19
	v_pk_fma_f32 v[104:105], v[4:5], v[2:3], v[104:105]
	v_lshlrev_b32_e32 v2, 16, v20
	v_and_b32_e32 v3, 0xffff0000, v20
	s_waitcnt lgkmcnt(0)
	v_pk_fma_f32 v[102:103], v[6:7], v[2:3], v[102:103]
	ds_read_b128 v[2:5], v167 offset:160
	v_lshlrev_b32_e32 v6, 16, v21
	v_and_b32_e32 v7, 0xffff0000, v21
	v_pk_fma_f32 v[100:101], v[8:9], v[6:7], v[100:101]
	ds_read_b128 v[6:9], v167 offset:176
	s_waitcnt vmcnt(2)
	v_lshlrev_b32_e32 v10, 16, v22
	v_and_b32_e32 v11, 0xffff0000, v22
	s_waitcnt lgkmcnt(1)
	v_pk_fma_f32 v[98:99], v[2:3], v[10:11], v[98:99]
	v_lshlrev_b32_e32 v2, 16, v23
	v_and_b32_e32 v3, 0xffff0000, v23
	v_pk_fma_f32 v[96:97], v[4:5], v[2:3], v[96:97]
	v_lshlrev_b32_e32 v2, 16, v24
	v_and_b32_e32 v3, 0xffff0000, v24
	s_waitcnt lgkmcnt(0)
	v_pk_fma_f32 v[94:95], v[6:7], v[2:3], v[94:95]
	ds_read_b128 v[2:5], v167 offset:192
	v_lshlrev_b32_e32 v6, 16, v25
	v_and_b32_e32 v7, 0xffff0000, v25
	v_pk_fma_f32 v[92:93], v[8:9], v[6:7], v[92:93]
	ds_read_b128 v[6:9], v167 offset:208
	s_waitcnt vmcnt(0)
	v_lshlrev_b32_e32 v10, 16, v46
	v_and_b32_e32 v11, 0xffff0000, v46
	s_waitcnt lgkmcnt(1)
	v_pk_fma_f32 v[90:91], v[2:3], v[10:11], v[90:91]
	v_lshlrev_b32_e32 v2, 16, v47
	v_and_b32_e32 v3, 0xffff0000, v47
	v_pk_fma_f32 v[88:89], v[4:5], v[2:3], v[88:89]
	v_lshlrev_b32_e32 v2, 16, v48
	v_and_b32_e32 v3, 0xffff0000, v48
	s_waitcnt lgkmcnt(0)
	v_pk_fma_f32 v[86:87], v[6:7], v[2:3], v[86:87]
	ds_read_b128 v[2:5], v167 offset:224
	v_lshlrev_b32_e32 v6, 16, v49
	v_and_b32_e32 v7, 0xffff0000, v49
	v_pk_fma_f32 v[84:85], v[8:9], v[6:7], v[84:85]
	ds_read_b128 v[6:9], v167 offset:240
	v_lshlrev_b32_e32 v10, 16, v42
	v_and_b32_e32 v11, 0xffff0000, v42
	s_waitcnt lgkmcnt(1)
	v_pk_fma_f32 v[82:83], v[2:3], v[10:11], v[82:83]
	v_lshlrev_b32_e32 v2, 16, v43
	v_and_b32_e32 v3, 0xffff0000, v43
	v_pk_fma_f32 v[80:81], v[4:5], v[2:3], v[80:81]
	v_lshlrev_b32_e32 v2, 16, v44
	v_and_b32_e32 v3, 0xffff0000, v44
	s_waitcnt lgkmcnt(0)
	v_pk_fma_f32 v[78:79], v[6:7], v[2:3], v[78:79]
	v_lshlrev_b32_e32 v2, 16, v45
	v_and_b32_e32 v3, 0xffff0000, v45
	v_pk_fma_f32 v[76:77], v[8:9], v[2:3], v[76:77]
	s_barrier
; __device__ __forceinline__ void store_row64_bf16(const float* v, u16* dst) {
; #pragma unroll
;   for (int q = 0; q < 8; ++q) {
;     uint4 o;
;     o.x = pack2(v[q * 8 + 0], v[q * 8 + 1]);
;     o.y = pack2(v[q * 8 + 2], v[q * 8 + 3]);
;     o.z = pack2(v[q * 8 + 4], v[q * 8 + 5]);
;     o.w = pack2(v[q * 8 + 6], v[q * 8 + 7]);
;     *(uint4*)(dst + q * 8) = o;
;   }
; __device__ __forceinline__ void merge_tile(const Params& P, int l, int mt, int nt, char* smem) {
;     ...
;   store_row64_bf16(macc, WSP(u16, OFF_M) + grow * DM + nt * 128 + half * 64);
	s_cbranch_scc1 .LBB0_1639
	v_lshlrev_b64 v[2:3], 11, v[108:109]
	v_lshl_add_u64 v[2:3], s[4:5], 0, v[2:3]
	v_lshl_add_u64 v[2:3], s[12:13], 1, v[2:3]
	v_mov_b32_e32 v75, v69
	v_lshl_add_u64 v[6:7], v[2:3], 0, v[74:75]
	v_cvt_pk_bf16_f32 v2, v146, v147
	v_cvt_pk_bf16_f32 v3, v144, v145
	v_cvt_pk_bf16_f32 v4, v142, v143
	v_cvt_pk_bf16_f32 v5, v140, v141
	global_store_dwordx4 v[6:7], v[2:5], off
	v_readlane_b32 s40, v253, 37
	v_readlane_b32 s48, v253, 45
	v_cvt_pk_bf16_f32 v2, v138, v139
	v_cvt_pk_bf16_f32 v3, v132, v133
	v_cvt_pk_bf16_f32 v4, v130, v131
	v_cvt_pk_bf16_f32 v5, v128, v129
	global_store_dwordx4 v[6:7], v[2:5], off offset:16
	v_readlane_b32 s49, v253, 46
	v_readlane_b32 s41, v253, 38
	v_cvt_pk_bf16_f32 v2, v126, v127
	v_cvt_pk_bf16_f32 v3, v124, v125
	v_cvt_pk_bf16_f32 v4, v122, v123
	v_cvt_pk_bf16_f32 v5, v120, v121
	global_store_dwordx4 v[6:7], v[2:5], off offset:32
	v_readlane_b32 s42, v253, 39
	v_readlane_b32 s43, v253, 40
	v_cvt_pk_bf16_f32 v2, v116, v117
	v_cvt_pk_bf16_f32 v3, v114, v115
	v_cvt_pk_bf16_f32 v4, v112, v113
	v_cvt_pk_bf16_f32 v5, v110, v111
	global_store_dwordx4 v[6:7], v[2:5], off offset:48
	v_readlane_b32 s44, v253, 41
	v_readlane_b32 s45, v253, 42
	v_cvt_pk_bf16_f32 v2, v106, v107
	v_cvt_pk_bf16_f32 v3, v104, v105
	v_cvt_pk_bf16_f32 v4, v102, v103
	v_cvt_pk_bf16_f32 v5, v100, v101
	global_store_dwordx4 v[6:7], v[2:5], off offset:64
	v_readlane_b32 s46, v253, 43
	v_readlane_b32 s47, v253, 44
	v_cvt_pk_bf16_f32 v2, v98, v99
	v_cvt_pk_bf16_f32 v3, v96, v97
	v_cvt_pk_bf16_f32 v4, v94, v95
	v_cvt_pk_bf16_f32 v5, v92, v93
	global_store_dwordx4 v[6:7], v[2:5], off offset:80
	v_readlane_b32 s50, v253, 47
	v_readlane_b32 s51, v253, 48
	v_cvt_pk_bf16_f32 v2, v90, v91
	v_cvt_pk_bf16_f32 v3, v88, v89
	v_cvt_pk_bf16_f32 v4, v86, v87
	v_cvt_pk_bf16_f32 v5, v84, v85
	global_store_dwordx4 v[6:7], v[2:5], off offset:96
	v_readlane_b32 s52, v253, 49
	v_readlane_b32 s53, v253, 50
	v_cvt_pk_bf16_f32 v2, v82, v83
	v_cvt_pk_bf16_f32 v3, v80, v81
	v_cvt_pk_bf16_f32 v4, v78, v79
	v_cvt_pk_bf16_f32 v5, v76, v77
	global_store_dwordx4 v[6:7], v[2:5], off offset:112
	v_readlane_b32 s54, v253, 51
	v_readlane_b32 s55, v253, 52
	s_branch .LBB0_1636
